# up-GEMM K-loop: LDS-DMA loads use SGPR-base addressing and the LDS fragment-read bases are hoisted (no VALU address math left in the load segments: 20 fewer VALU per two K-tiles); on top of the norm-p
# baseline (speedup 1.0000x reference)
; #define PG8_STAGE(bufoff, gbase, voff) do { _Pragma("unroll") for (int _i = 0; _i < 2; ++_i) \
;         __builtin_amdgcn_global_load_lds((const unsigned*)((const char*)(gbase) + (voff)[_i]), (PG8_LAS unsigned*)(lds + (bufoff) + ldsw + _i * 8192), 16, 0, 0); } while (0)
; #define PG8_LDA(dst, b, h) do { _Pragma("unroll") for (int m = 0; m < 4; ++m) _Pragma("unroll") for (int k = 0; k < 2; ++k) dst[m][k] = *(const PG8_LAS bf16x8*)(lds + PG8_SA(b, h) + aoff + m * 2048 + k * 1024); } while (0)
; #define PG8_LDB(dst, b, h) do { _Pragma("unroll") for (int n = 0; n < 2; ++n) _Pragma("unroll") for (int k = 0; k < 2; ++k) dst[n][k] = *(const PG8_LAS bf16x8*)(lds + PG8_SB(b, h) + boff + n * 2048 + k * 1024); } while (0)
; #define PG8_WAIT_V(n) asm volatile("s_waitcnt vmcnt(" #n ")" ::: "memory")
; #define PG8_WAIT_L(n) asm volatile("s_waitcnt lgkmcnt(" #n ")" ::: "memory")
; #define PG8_BAR __builtin_amdgcn_s_barrier()
; #define PG8_SCHED __builtin_amdgcn_sched_barrier(0)
; template <class Epi, class Sched, bool ALIGN_EPI = false, bool SP2 = false>
; __device__ __forceinline__ void gemm_phase(PG8_LAS unsigned char* lds, const Gemm g, const Sched& S, const Epi& E) {
;     ...
;     f32x4 acc[2][2][4][2];
; #pragma unroll
;     for (int a = 0; a < 2; ++a)
; #pragma unroll
;         for (int b = 0; b < 2; ++b)
; #pragma unroll
;             for (int m = 0; m < 4; ++m)
; #pragma unroll
;                 for (int n = 0; n < 2; ++n) acc[a][b][m][n] = (f32x4){0.f, 0.f, 0.f, 0.f};
;     ...
;         const bool has_next = S.next(ui + 1, nxt);
;         const char* nA = has_next ? (const char*)g.A + (size_t)nxt.pm * tstep : cA; const char* nB = has_next ? (const char*)g.Bt + (size_t)nxt.pn * tstep : cB;
;         for (int t = 0; t < nt; t += 2) {
;             const bool last = (t == nt - 2);
;             const char* a1 = cA + (size_t)(t + 1) * kstep;
;             const char* a2 = last ? nA : cA + (size_t)(t + 2) * kstep; const char* b2 = last ? nB : cB + (size_t)(t + 2) * kstep;
;             const char* a3 = a2 + kstep; const char* b3 = b2 + kstep;
;             if (last && has_next) S.a_ready(nxt);
;             if constexpr (SP2) {
;             PG8_LDB(B0, 0, 0); PG8_LDB(B1, 0, 1); PG8_SCHED; PG8_LDA(At, 0, 0); PG8_STAGE(PG8_SA(1, 1), a1 + hstep, voffA);
;             PG8_WAIT_V(8); PG8_WAIT_L(0); PG8_BAR; PG8_MMA(0, 0, At, B0); PG8_MMA(0, 1, At, B1); PG8_BAR; PG8_SCHED;
.LBB0_54:
	s_ashr_i32 s27, s26, 31
	s_lshl_b64 s[28:29], s[26:27], 20
	s_add_u32 s36, s74, s28
	s_addc_u32 s37, s75, s29
	s_and_b64 s[28:29], s[40:41], exec
	s_cselect_b32 s27, s37, s43
	s_cselect_b32 s65, s36, s42
	s_ashr_i32 s25, s24, 31
	s_lshl_b64 s[28:29], s[24:25], 20
	s_add_u32 s38, s2, s28
	s_addc_u32 s39, s7, s29
	s_and_b64 s[28:29], s[40:41], exec
	s_cselect_b32 s25, s39, s51
	s_cselect_b32 s66, s38, s50
	s_add_u32 s42, s42, 0x80080
	s_addc_u32 s43, s43, 0
	s_add_u32 s67, s50, 0x100
	v_mov_b32_e32 v0, 0
	s_addc_u32 s70, s51, 0
	s_mov_b32 s71, -2
	v_mov_b32_e32 v1, v0
	v_mov_b32_e32 v2, v0
	v_mov_b32_e32 v3, v0
	v_mov_b32_e32 v4, v0
	v_mov_b32_e32 v5, v0
	v_mov_b32_e32 v6, v0
	v_mov_b32_e32 v7, v0
	v_mov_b32_e32 v16, v0
	v_mov_b32_e32 v17, v0
	v_mov_b32_e32 v18, v0
	v_mov_b32_e32 v19, v0
	v_mov_b32_e32 v20, v0
	v_mov_b32_e32 v21, v0
	v_mov_b32_e32 v22, v0
	v_mov_b32_e32 v23, v0
	v_mov_b32_e32 v32, v0
	v_mov_b32_e32 v33, v0
	v_mov_b32_e32 v34, v0
	v_mov_b32_e32 v35, v0
	v_mov_b32_e32 v36, v0
	v_mov_b32_e32 v37, v0
	v_mov_b32_e32 v38, v0
	v_mov_b32_e32 v39, v0
	v_mov_b32_e32 v48, v0
	v_mov_b32_e32 v49, v0
	v_mov_b32_e32 v50, v0
	v_mov_b32_e32 v51, v0
	v_mov_b32_e32 v52, v0
	v_mov_b32_e32 v53, v0
	v_mov_b32_e32 v54, v0
	v_mov_b32_e32 v55, v0
	v_mov_b32_e32 v8, v0
	v_mov_b32_e32 v9, v0
	v_mov_b32_e32 v10, v0
	v_mov_b32_e32 v11, v0
	v_mov_b32_e32 v12, v0
	v_mov_b32_e32 v13, v0
	v_mov_b32_e32 v14, v0
	v_mov_b32_e32 v15, v0
	v_mov_b32_e32 v24, v0
	v_mov_b32_e32 v25, v0
	v_mov_b32_e32 v26, v0
	v_mov_b32_e32 v27, v0
	v_mov_b32_e32 v28, v0
	v_mov_b32_e32 v29, v0
	v_mov_b32_e32 v30, v0
	v_mov_b32_e32 v31, v0
	v_mov_b32_e32 v40, v0
	v_mov_b32_e32 v41, v0
	v_mov_b32_e32 v42, v0
	v_mov_b32_e32 v43, v0
	v_mov_b32_e32 v44, v0
	v_mov_b32_e32 v45, v0
	v_mov_b32_e32 v46, v0
	v_mov_b32_e32 v47, v0
	v_mov_b32_e32 v56, v0
	v_mov_b32_e32 v57, v0
	v_mov_b32_e32 v58, v0
	v_mov_b32_e32 v59, v0
	v_mov_b32_e32 v60, v0
	v_mov_b32_e32 v61, v0
	v_mov_b32_e32 v62, v0
	v_mov_b32_e32 v63, v0
	v_mov_b32_e32 v80, v0
	v_mov_b32_e32 v81, v0
	v_mov_b32_e32 v82, v0
	v_mov_b32_e32 v83, v0
	v_mov_b32_e32 v84, v0
	v_mov_b32_e32 v85, v0
	v_mov_b32_e32 v86, v0
	v_mov_b32_e32 v87, v0
	v_mov_b32_e32 v96, v0
	v_mov_b32_e32 v97, v0
	v_mov_b32_e32 v98, v0
	v_mov_b32_e32 v99, v0
	v_mov_b32_e32 v100, v0
	v_mov_b32_e32 v101, v0
	v_mov_b32_e32 v102, v0
	v_mov_b32_e32 v103, v0
	v_mov_b32_e32 v112, v0
	v_mov_b32_e32 v113, v0
	v_mov_b32_e32 v114, v0
	v_mov_b32_e32 v115, v0
	v_mov_b32_e32 v116, v0
	v_mov_b32_e32 v117, v0
	v_mov_b32_e32 v118, v0
	v_mov_b32_e32 v119, v0
	v_mov_b32_e32 v128, v0
	v_mov_b32_e32 v129, v0
	v_mov_b32_e32 v130, v0
	v_mov_b32_e32 v131, v0
	v_mov_b32_e32 v132, v0
	v_mov_b32_e32 v133, v0
	v_mov_b32_e32 v134, v0
	v_mov_b32_e32 v135, v0
	v_mov_b32_e32 v88, v0
	v_mov_b32_e32 v89, v0
	v_mov_b32_e32 v90, v0
	v_mov_b32_e32 v91, v0
	v_mov_b32_e32 v92, v0
	v_mov_b32_e32 v93, v0
	v_mov_b32_e32 v94, v0
	v_mov_b32_e32 v95, v0
	v_mov_b32_e32 v104, v0
	v_mov_b32_e32 v105, v0
	v_mov_b32_e32 v106, v0
	v_mov_b32_e32 v107, v0
	v_mov_b32_e32 v108, v0
	v_mov_b32_e32 v109, v0
	v_mov_b32_e32 v110, v0
	v_mov_b32_e32 v111, v0
	v_mov_b32_e32 v120, v0
	v_mov_b32_e32 v121, v0
	v_mov_b32_e32 v122, v0
	v_mov_b32_e32 v123, v0
	v_mov_b32_e32 v124, v0
	v_mov_b32_e32 v125, v0
	v_mov_b32_e32 v126, v0
	v_mov_b32_e32 v127, v0
	v_mov_b32_e32 v136, v0
	v_mov_b32_e32 v137, v0
	v_mov_b32_e32 v138, v0
	v_mov_b32_e32 v139, v0
	v_mov_b32_e32 v140, v0
	v_mov_b32_e32 v141, v0
	v_mov_b32_e32 v142, v0
	v_mov_b32_e32 v143, v0
	s_nop 0
	s_nop 0
	s_nop 0
	s_nop 0
	s_nop 0
	s_nop 0
	s_nop 0
	s_nop 0
	v_add_u32_e32 v192, 0x10000, v163
	v_add_u32_e32 v193, 0x14000, v163
	v_add_u32_e32 v212, 0x18000, v163
	v_add_u32_e32 v213, 0x1c000, v163
.LBB0_55:
	s_add_u32 s28, s42, 0xfff80080
	s_addc_u32 s29, s43, -1
	s_add_i32 s72, 0, 0x10000
	s_cmp_eq_u32 s71, 28
	s_cselect_b32 s53, s27, s29
	s_cselect_b32 s52, s65, s28
	s_cselect_b32 s51, s25, s70
	s_cselect_b32 s50, s66, s67
	s_add_i32 s73, 0, 0x14000
	ds_read_b128 v[64:67], v192
	ds_read_b128 v[68:71], v192 offset:1024
	ds_read_b128 v[72:75], v192 offset:2048
	ds_read_b128 v[76:79], v192 offset:3072
	ds_read_b128 v[156:159], v193
	ds_read_b128 v[168:171], v193 offset:1024
	ds_read_b128 v[172:175], v193 offset:2048
	ds_read_b128 v[176:179], v193 offset:3072
	s_add_i32 m0, s12, 0xc000
	ds_read_b128 v[180:183], v165
	ds_read_b128 v[184:187], v165 offset:1024
	ds_read_b128 v[188:191], v165 offset:2048
	ds_read_b128 v[196:199], v165 offset:3072
	ds_read_b128 v[200:203], v165 offset:4096
	ds_read_b128 v[204:207], v165 offset:5120
	ds_read_b128 v[208:211], v165 offset:6144
	ds_read_b128 v[222:225], v165 offset:7168
	global_load_lds_dwordx4 v152, s[42:43]
	s_add_i32 m0, s12, 0xe000
	s_nop 0
	global_load_lds_dwordx4 v154, s[42:43]
	s_waitcnt vmcnt(8)
	s_waitcnt lgkmcnt(0)
	s_barrier
; #define PG8_STAGE(bufoff, gbase, voff) do { _Pragma("unroll") for (int _i = 0; _i < 2; ++_i) \
;         __builtin_amdgcn_global_load_lds((const unsigned*)((const char*)(gbase) + (voff)[_i]), (PG8_LAS unsigned*)(lds + (bufoff) + ldsw + _i * 8192), 16, 0, 0); } while (0)
; #define PG8_LDA(dst, b, h) do { _Pragma("unroll") for (int m = 0; m < 4; ++m) _Pragma("unroll") for (int k = 0; k < 2; ++k) dst[m][k] = *(const PG8_LAS bf16x8*)(lds + PG8_SA(b, h) + aoff + m * 2048 + k * 1024); } while (0)
; #define PG8_MMA(ai, bj, At, Bt) do { __builtin_amdgcn_s_setprio(1); _Pragma("unroll") for (int m = 0; m < 4; ++m) _Pragma("unroll") for (int n = 0; n < 2; ++n) _Pragma("unroll") for (int k = 0; k < 2; ++k) \
;         acc[ai][bj][m][n] = __builtin_amdgcn_mfma_f32_16x16x32_bf16(Bt[n][k], At[m][k], acc[ai][bj][m][n], 0, 0, 0); __builtin_amdgcn_s_setprio(0); } while (0)
; #define PG8_WAIT_V(n) asm volatile("s_waitcnt vmcnt(" #n ")" ::: "memory")
; #define PG8_WAIT_L(n) asm volatile("s_waitcnt lgkmcnt(" #n ")" ::: "memory")
; #define PG8_BAR __builtin_amdgcn_s_barrier()
; #define PG8_SCHED __builtin_amdgcn_sched_barrier(0)
; template <class Epi, class Sched, bool ALIGN_EPI = false, bool SP2 = false>
; __device__ __forceinline__ void gemm_phase(PG8_LAS unsigned char* lds, const Gemm g, const Sched& S, const Epi& E) {
;     ...
;             PG8_WAIT_V(8); PG8_WAIT_L(0); PG8_BAR; PG8_MMA(0, 0, At, B0); PG8_MMA(0, 1, At, B1); PG8_BAR; PG8_SCHED;
;             PG8_LDA(At, 0, 1); PG8_STAGE(PG8_SB(0, 0), b2, voffB); PG8_STAGE(PG8_SB(0, 1), b2 + hstep, voffB); PG8_STAGE(PG8_SA(0, 0), a2, voffA);
;             PG8_WAIT_V(8); PG8_WAIT_L(0); PG8_BAR; PG8_MMA(1, 0, At, B0); PG8_MMA(1, 1, At, B1); PG8_BAR; PG8_SCHED;
	s_setprio 1
	s_waitcnt lgkmcnt(0)
	v_mfma_f32_16x16x32_bf16 v[140:143], v[64:67], v[180:183], v[140:143]
	v_mfma_f32_16x16x32_bf16 v[136:139], v[72:75], v[180:183], v[136:139]
	v_mfma_f32_16x16x32_bf16 v[124:127], v[64:67], v[188:191], v[124:127]
	v_mfma_f32_16x16x32_bf16 v[120:123], v[72:75], v[188:191], v[120:123]
	v_mfma_f32_16x16x32_bf16 v[108:111], v[64:67], v[200:203], v[108:111]
	v_mfma_f32_16x16x32_bf16 v[104:107], v[72:75], v[200:203], v[104:107]
	v_mfma_f32_16x16x32_bf16 v[92:95], v[64:67], v[208:211], v[92:95]
	v_mfma_f32_16x16x32_bf16 v[88:91], v[72:75], v[208:211], v[88:91]
	v_mfma_f32_16x16x32_bf16 v[140:143], v[68:71], v[184:187], v[140:143]
	v_mfma_f32_16x16x32_bf16 v[136:139], v[76:79], v[184:187], v[136:139]
	v_mfma_f32_16x16x32_bf16 v[124:127], v[68:71], v[196:199], v[124:127]
	v_mfma_f32_16x16x32_bf16 v[120:123], v[76:79], v[196:199], v[120:123]
	v_mfma_f32_16x16x32_bf16 v[108:111], v[68:71], v[204:207], v[108:111]
	v_mfma_f32_16x16x32_bf16 v[104:107], v[76:79], v[204:207], v[104:107]
	v_mfma_f32_16x16x32_bf16 v[92:95], v[68:71], v[222:225], v[92:95]
	v_mfma_f32_16x16x32_bf16 v[88:91], v[76:79], v[222:225], v[88:91]
	s_setprio 0
	s_setprio 1
	v_mfma_f32_16x16x32_bf16 v[132:135], v[156:159], v[180:183], v[132:135]
	v_mfma_f32_16x16x32_bf16 v[128:131], v[172:175], v[180:183], v[128:131]
	v_mfma_f32_16x16x32_bf16 v[116:119], v[156:159], v[188:191], v[116:119]
	v_mfma_f32_16x16x32_bf16 v[112:115], v[172:175], v[188:191], v[112:115]
	v_mfma_f32_16x16x32_bf16 v[100:103], v[156:159], v[200:203], v[100:103]
	v_mfma_f32_16x16x32_bf16 v[96:99], v[172:175], v[200:203], v[96:99]
	v_mfma_f32_16x16x32_bf16 v[84:87], v[156:159], v[208:211], v[84:87]
	v_mfma_f32_16x16x32_bf16 v[80:83], v[172:175], v[208:211], v[80:83]
	v_mfma_f32_16x16x32_bf16 v[132:135], v[168:171], v[184:187], v[132:135]
	v_mfma_f32_16x16x32_bf16 v[128:131], v[176:179], v[184:187], v[128:131]
	v_mfma_f32_16x16x32_bf16 v[116:119], v[168:171], v[196:199], v[116:119]
	v_mfma_f32_16x16x32_bf16 v[112:115], v[176:179], v[196:199], v[112:115]
	v_mfma_f32_16x16x32_bf16 v[100:103], v[168:171], v[204:207], v[100:103]
	v_mfma_f32_16x16x32_bf16 v[96:99], v[176:179], v[204:207], v[96:99]
	v_mfma_f32_16x16x32_bf16 v[84:87], v[168:171], v[222:225], v[84:87]
	v_mfma_f32_16x16x32_bf16 v[80:83], v[176:179], v[222:225], v[80:83]
	s_setprio 0
	s_barrier
	s_add_i32 s28, s72, s8
	s_mov_b32 m0, s28
	ds_read_b128 v[180:183], v165 offset:16384
	ds_read_b128 v[184:187], v165 offset:17408
	ds_read_b128 v[188:191], v165 offset:18432
	ds_read_b128 v[196:199], v165 offset:19456
	ds_read_b128 v[200:203], v165 offset:20480
	ds_read_b128 v[204:207], v165 offset:21504
	ds_read_b128 v[208:211], v165 offset:22528
	ds_read_b128 v[222:225], v165 offset:23552
	global_load_lds_dwordx4 v194, s[50:51]
	s_add_i32 m0, s28, 0x2000
	s_add_u32 s28, s50, 0x80000
	s_addc_u32 s29, s51, 0
	s_add_i32 s72, s73, s8
	global_load_lds_dwordx4 v144, s[50:51]
	s_mov_b32 m0, s72
	s_nop 0
	global_load_lds_dwordx4 v194, s[28:29]
	s_add_i32 m0, s72, 0x2000
	s_nop 0
	global_load_lds_dwordx4 v144, s[28:29]
	s_mov_b32 m0, s12
	s_nop 0
	global_load_lds_dwordx4 v148, s[52:53]
	s_mov_b32 m0, s20
	s_nop 0
	global_load_lds_dwordx4 v146, s[52:53]
	s_waitcnt vmcnt(8)
	s_waitcnt lgkmcnt(0)
	s_barrier
	s_setprio 1
	s_waitcnt lgkmcnt(0)
	v_mfma_f32_16x16x32_bf16 v[60:63], v[64:67], v[180:183], v[60:63]
	v_mfma_f32_16x16x32_bf16 v[56:59], v[72:75], v[180:183], v[56:59]
	v_mfma_f32_16x16x32_bf16 v[44:47], v[64:67], v[188:191], v[44:47]
	v_mfma_f32_16x16x32_bf16 v[40:43], v[72:75], v[188:191], v[40:43]
	v_mfma_f32_16x16x32_bf16 v[28:31], v[64:67], v[200:203], v[28:31]
	v_mfma_f32_16x16x32_bf16 v[24:27], v[72:75], v[200:203], v[24:27]
	v_mfma_f32_16x16x32_bf16 v[12:15], v[64:67], v[208:211], v[12:15]
	v_mfma_f32_16x16x32_bf16 v[8:11], v[72:75], v[208:211], v[8:11]
	v_mfma_f32_16x16x32_bf16 v[60:63], v[68:71], v[184:187], v[60:63]
	v_mfma_f32_16x16x32_bf16 v[56:59], v[76:79], v[184:187], v[56:59]
	v_mfma_f32_16x16x32_bf16 v[44:47], v[68:71], v[196:199], v[44:47]
	v_mfma_f32_16x16x32_bf16 v[40:43], v[76:79], v[196:199], v[40:43]
	v_mfma_f32_16x16x32_bf16 v[28:31], v[68:71], v[204:207], v[28:31]
	v_mfma_f32_16x16x32_bf16 v[24:27], v[76:79], v[204:207], v[24:27]
	v_mfma_f32_16x16x32_bf16 v[12:15], v[68:71], v[222:225], v[12:15]
	v_mfma_f32_16x16x32_bf16 v[8:11], v[76:79], v[222:225], v[8:11]
	s_setprio 0
	s_setprio 1
	v_mfma_f32_16x16x32_bf16 v[52:55], v[156:159], v[180:183], v[52:55]
	v_mfma_f32_16x16x32_bf16 v[48:51], v[172:175], v[180:183], v[48:51]
	v_mfma_f32_16x16x32_bf16 v[36:39], v[156:159], v[188:191], v[36:39]
	v_mfma_f32_16x16x32_bf16 v[32:35], v[172:175], v[188:191], v[32:35]
	v_mfma_f32_16x16x32_bf16 v[20:23], v[156:159], v[200:203], v[20:23]
	v_mfma_f32_16x16x32_bf16 v[16:19], v[172:175], v[200:203], v[16:19]
	v_mfma_f32_16x16x32_bf16 v[4:7], v[156:159], v[208:211], v[4:7]
	v_mfma_f32_16x16x32_bf16 v[0:3], v[172:175], v[208:211], v[0:3]
	v_mfma_f32_16x16x32_bf16 v[52:55], v[168:171], v[184:187], v[52:55]
	v_mfma_f32_16x16x32_bf16 v[48:51], v[176:179], v[184:187], v[48:51]
	v_mfma_f32_16x16x32_bf16 v[36:39], v[168:171], v[196:199], v[36:39]
	v_mfma_f32_16x16x32_bf16 v[32:35], v[176:179], v[196:199], v[32:35]
	v_mfma_f32_16x16x32_bf16 v[20:23], v[168:171], v[204:207], v[20:23]
	v_mfma_f32_16x16x32_bf16 v[16:19], v[176:179], v[204:207], v[16:19]
	v_mfma_f32_16x16x32_bf16 v[4:7], v[168:171], v[222:225], v[4:7]
	v_mfma_f32_16x16x32_bf16 v[0:3], v[176:179], v[222:225], v[0:3]
	s_setprio 0
	s_barrier
; #define PG8_STAGE(bufoff, gbase, voff) do { _Pragma("unroll") for (int _i = 0; _i < 2; ++_i) \
;         __builtin_amdgcn_global_load_lds((const unsigned*)((const char*)(gbase) + (voff)[_i]), (PG8_LAS unsigned*)(lds + (bufoff) + ldsw + _i * 8192), 16, 0, 0); } while (0)
; #define PG8_LDA(dst, b, h) do { _Pragma("unroll") for (int m = 0; m < 4; ++m) _Pragma("unroll") for (int k = 0; k < 2; ++k) dst[m][k] = *(const PG8_LAS bf16x8*)(lds + PG8_SA(b, h) + aoff + m * 2048 + k * 1024); } while (0)
; #define PG8_LDB(dst, b, h) do { _Pragma("unroll") for (int n = 0; n < 2; ++n) _Pragma("unroll") for (int k = 0; k < 2; ++k) dst[n][k] = *(const PG8_LAS bf16x8*)(lds + PG8_SB(b, h) + boff + n * 2048 + k * 1024); } while (0)
; #define PG8_MMA(ai, bj, At, Bt) do { __builtin_amdgcn_s_setprio(1); _Pragma("unroll") for (int m = 0; m < 4; ++m) _Pragma("unroll") for (int n = 0; n < 2; ++n) _Pragma("unroll") for (int k = 0; k < 2; ++k) \
;         acc[ai][bj][m][n] = __builtin_amdgcn_mfma_f32_16x16x32_bf16(Bt[n][k], At[m][k], acc[ai][bj][m][n], 0, 0, 0); __builtin_amdgcn_s_setprio(0); } while (0)
; #define PG8_WAIT_V(n) asm volatile("s_waitcnt vmcnt(" #n ")" ::: "memory")
; #define PG8_WAIT_L(n) asm volatile("s_waitcnt lgkmcnt(" #n ")" ::: "memory")
; #define PG8_BAR __builtin_amdgcn_s_barrier()
; #define PG8_SCHED __builtin_amdgcn_sched_barrier(0)
; template <class Epi, class Sched, bool ALIGN_EPI = false, bool SP2 = false>
; __device__ __forceinline__ void gemm_phase(PG8_LAS unsigned char* lds, const Gemm g, const Sched& S, const Epi& E) {
;     ...
;             PG8_LDB(B0, 1, 0); PG8_LDB(B1, 1, 1); PG8_SCHED; PG8_LDA(At, 1, 0); PG8_STAGE(PG8_SA(0, 1), a2 + hstep, voffA);
;             PG8_WAIT_V(8); PG8_WAIT_L(0); PG8_BAR; PG8_MMA(0, 0, At, B0); PG8_MMA(0, 1, At, B1); PG8_BAR; PG8_SCHED;
;             PG8_LDA(At, 1, 1); PG8_STAGE(PG8_SB(1, 0), b3, voffB); PG8_STAGE(PG8_SB(1, 1), b3 + hstep, voffB); PG8_STAGE(PG8_SA(1, 0), a3, voffA);
;             PG8_WAIT_V(8); PG8_WAIT_L(0); PG8_BAR; PG8_MMA(1, 0, At, B0); PG8_MMA(1, 1, At, B1); PG8_BAR; PG8_SCHED;
;     ...
;         if constexpr (ALIGN_EPI) { if (wr == 0) PG8_BAR; }
	s_add_i32 s72, 0, 0x18000
	s_add_i32 s73, 0, 0x1c000
	ds_read_b128 v[64:67], v212
	ds_read_b128 v[68:71], v212 offset:1024
	ds_read_b128 v[72:75], v212 offset:2048
	ds_read_b128 v[76:79], v212 offset:3072
	ds_read_b128 v[156:159], v213
	ds_read_b128 v[168:171], v213 offset:1024
	ds_read_b128 v[172:175], v213 offset:2048
	ds_read_b128 v[176:179], v213 offset:3072
	s_add_u32 s28, s52, 0x80000
	s_addc_u32 s29, s53, 0
	s_mov_b32 m0, s21
	ds_read_b128 v[180:183], v165 offset:32768
	ds_read_b128 v[184:187], v165 offset:33792
	ds_read_b128 v[188:191], v165 offset:34816
	ds_read_b128 v[196:199], v165 offset:35840
	ds_read_b128 v[200:203], v165 offset:36864
	ds_read_b128 v[204:207], v165 offset:37888
	ds_read_b128 v[208:211], v165 offset:38912
	ds_read_b128 v[222:225], v165 offset:39936
	global_load_lds_dwordx4 v148, s[28:29]
	s_mov_b32 m0, s48
	s_nop 0
	global_load_lds_dwordx4 v146, s[28:29]
	s_waitcnt vmcnt(8)
	s_waitcnt lgkmcnt(0)
	s_barrier
	s_setprio 1
	s_waitcnt lgkmcnt(0)
	v_mfma_f32_16x16x32_bf16 v[140:143], v[64:67], v[180:183], v[140:143]
	v_mfma_f32_16x16x32_bf16 v[136:139], v[72:75], v[180:183], v[136:139]
	v_mfma_f32_16x16x32_bf16 v[124:127], v[64:67], v[188:191], v[124:127]
	v_mfma_f32_16x16x32_bf16 v[120:123], v[72:75], v[188:191], v[120:123]
	v_mfma_f32_16x16x32_bf16 v[108:111], v[64:67], v[200:203], v[108:111]
	v_mfma_f32_16x16x32_bf16 v[104:107], v[72:75], v[200:203], v[104:107]
	v_mfma_f32_16x16x32_bf16 v[92:95], v[64:67], v[208:211], v[92:95]
	v_mfma_f32_16x16x32_bf16 v[88:91], v[72:75], v[208:211], v[88:91]
	v_mfma_f32_16x16x32_bf16 v[140:143], v[68:71], v[184:187], v[140:143]
	v_mfma_f32_16x16x32_bf16 v[136:139], v[76:79], v[184:187], v[136:139]
	v_mfma_f32_16x16x32_bf16 v[124:127], v[68:71], v[196:199], v[124:127]
	v_mfma_f32_16x16x32_bf16 v[120:123], v[76:79], v[196:199], v[120:123]
	v_mfma_f32_16x16x32_bf16 v[108:111], v[68:71], v[204:207], v[108:111]
	v_mfma_f32_16x16x32_bf16 v[104:107], v[76:79], v[204:207], v[104:107]
	v_mfma_f32_16x16x32_bf16 v[92:95], v[68:71], v[222:225], v[92:95]
	v_mfma_f32_16x16x32_bf16 v[88:91], v[76:79], v[222:225], v[88:91]
	s_setprio 0
	s_setprio 1
	v_mfma_f32_16x16x32_bf16 v[132:135], v[156:159], v[180:183], v[132:135]
	v_mfma_f32_16x16x32_bf16 v[128:131], v[172:175], v[180:183], v[128:131]
	v_mfma_f32_16x16x32_bf16 v[116:119], v[156:159], v[188:191], v[116:119]
	v_mfma_f32_16x16x32_bf16 v[112:115], v[172:175], v[188:191], v[112:115]
	v_mfma_f32_16x16x32_bf16 v[100:103], v[156:159], v[200:203], v[100:103]
	v_mfma_f32_16x16x32_bf16 v[96:99], v[172:175], v[200:203], v[96:99]
	v_mfma_f32_16x16x32_bf16 v[84:87], v[156:159], v[208:211], v[84:87]
	v_mfma_f32_16x16x32_bf16 v[80:83], v[172:175], v[208:211], v[80:83]
	v_mfma_f32_16x16x32_bf16 v[132:135], v[168:171], v[184:187], v[132:135]
	v_mfma_f32_16x16x32_bf16 v[128:131], v[176:179], v[184:187], v[128:131]
	v_mfma_f32_16x16x32_bf16 v[116:119], v[168:171], v[196:199], v[116:119]
	v_mfma_f32_16x16x32_bf16 v[112:115], v[176:179], v[196:199], v[112:115]
	v_mfma_f32_16x16x32_bf16 v[100:103], v[168:171], v[204:207], v[100:103]
	v_mfma_f32_16x16x32_bf16 v[96:99], v[176:179], v[204:207], v[96:99]
	v_mfma_f32_16x16x32_bf16 v[84:87], v[168:171], v[222:225], v[84:87]
	v_mfma_f32_16x16x32_bf16 v[80:83], v[176:179], v[222:225], v[80:83]
	s_setprio 0
	s_barrier
	s_add_i32 s28, s72, s8
	s_add_u32 s98, s50, 0x80
	s_addc_u32 s99, s51, 0
	s_mov_b32 m0, s28
	ds_read_b128 v[180:183], v165 offset:49152
	ds_read_b128 v[184:187], v165 offset:50176
	ds_read_b128 v[188:191], v165 offset:51200
	ds_read_b128 v[196:199], v165 offset:52224
	ds_read_b128 v[200:203], v165 offset:53248
	ds_read_b128 v[204:207], v165 offset:54272
	ds_read_b128 v[208:211], v165 offset:55296
	ds_read_b128 v[222:225], v165 offset:56320
	global_load_lds_dwordx4 v194, s[98:99]
	s_add_i32 m0, s28, 0x2000
	s_add_u32 s28, s50, 0x80080
	s_addc_u32 s29, s51, 0
	s_add_i32 s50, s73, s8
	global_load_lds_dwordx4 v144, s[98:99]
	s_mov_b32 m0, s50
	s_add_u32 s100, s52, 0x80
	s_addc_u32 s101, s53, 0
	global_load_lds_dwordx4 v194, s[28:29]
	s_add_i32 m0, s50, 0x2000
	s_nop 0
	global_load_lds_dwordx4 v144, s[28:29]
	s_mov_b32 m0, s55
	s_nop 0
	global_load_lds_dwordx4 v148, s[100:101]
	s_mov_b32 m0, s60
	s_nop 0
	global_load_lds_dwordx4 v146, s[100:101]
	s_waitcnt vmcnt(8)
	s_waitcnt lgkmcnt(0)
	s_barrier
	s_setprio 1
	s_waitcnt lgkmcnt(0)
	v_mfma_f32_16x16x32_bf16 v[60:63], v[64:67], v[180:183], v[60:63]
	v_mfma_f32_16x16x32_bf16 v[56:59], v[72:75], v[180:183], v[56:59]
	v_mfma_f32_16x16x32_bf16 v[44:47], v[64:67], v[188:191], v[44:47]
	v_mfma_f32_16x16x32_bf16 v[40:43], v[72:75], v[188:191], v[40:43]
	v_mfma_f32_16x16x32_bf16 v[28:31], v[64:67], v[200:203], v[28:31]
	v_mfma_f32_16x16x32_bf16 v[24:27], v[72:75], v[200:203], v[24:27]
	v_mfma_f32_16x16x32_bf16 v[12:15], v[64:67], v[208:211], v[12:15]
	v_mfma_f32_16x16x32_bf16 v[8:11], v[72:75], v[208:211], v[8:11]
	v_mfma_f32_16x16x32_bf16 v[60:63], v[68:71], v[184:187], v[60:63]
	v_mfma_f32_16x16x32_bf16 v[56:59], v[76:79], v[184:187], v[56:59]
	v_mfma_f32_16x16x32_bf16 v[44:47], v[68:71], v[196:199], v[44:47]
	v_mfma_f32_16x16x32_bf16 v[40:43], v[76:79], v[196:199], v[40:43]
	v_mfma_f32_16x16x32_bf16 v[28:31], v[68:71], v[204:207], v[28:31]
	v_mfma_f32_16x16x32_bf16 v[24:27], v[76:79], v[204:207], v[24:27]
	v_mfma_f32_16x16x32_bf16 v[12:15], v[68:71], v[222:225], v[12:15]
	v_mfma_f32_16x16x32_bf16 v[8:11], v[76:79], v[222:225], v[8:11]
	s_setprio 0
	s_setprio 1
	v_mfma_f32_16x16x32_bf16 v[52:55], v[156:159], v[180:183], v[52:55]
	v_mfma_f32_16x16x32_bf16 v[48:51], v[172:175], v[180:183], v[48:51]
	v_mfma_f32_16x16x32_bf16 v[36:39], v[156:159], v[188:191], v[36:39]
	v_mfma_f32_16x16x32_bf16 v[32:35], v[172:175], v[188:191], v[32:35]
	v_mfma_f32_16x16x32_bf16 v[20:23], v[156:159], v[200:203], v[20:23]
	v_mfma_f32_16x16x32_bf16 v[16:19], v[172:175], v[200:203], v[16:19]
	v_mfma_f32_16x16x32_bf16 v[4:7], v[156:159], v[208:211], v[4:7]
	v_mfma_f32_16x16x32_bf16 v[0:3], v[172:175], v[208:211], v[0:3]
	v_mfma_f32_16x16x32_bf16 v[52:55], v[168:171], v[184:187], v[52:55]
	v_mfma_f32_16x16x32_bf16 v[48:51], v[176:179], v[184:187], v[48:51]
	v_mfma_f32_16x16x32_bf16 v[36:39], v[168:171], v[196:199], v[36:39]
	v_mfma_f32_16x16x32_bf16 v[32:35], v[176:179], v[196:199], v[32:35]
	v_mfma_f32_16x16x32_bf16 v[20:23], v[168:171], v[204:207], v[20:23]
	v_mfma_f32_16x16x32_bf16 v[16:19], v[176:179], v[204:207], v[16:19]
	v_mfma_f32_16x16x32_bf16 v[4:7], v[168:171], v[222:225], v[4:7]
	v_mfma_f32_16x16x32_bf16 v[0:3], v[176:179], v[222:225], v[0:3]
	s_setprio 0
	s_barrier
	s_add_i32 s71, s71, 2
	s_add_u32 s42, s42, 0x100
	s_addc_u32 s43, s43, 0
	s_add_u32 s67, s67, 0x100
	s_addc_u32 s70, s70, 0
	s_cmp_gt_u32 s71, 29
	s_cbranch_scc0 .LBB0_55
	s_and_b64 vcc, exec, s[22:23]
	s_cbranch_vccz .LBB0_58
	s_barrier
;     __device__ __forceinline__ void operator()(const f32x4 (&acc)[2][2][4][2], const Unit& u, int wr, int wc, int fr, int fq) const {
;     ...
;         if (ss) { const float* swp = sw + (size_t)((u.pm * BM) / rows_per_batch) * sw_stride + u.pn * BM + wc * 32 + 8 * fq;
; #pragma unroll
;             for (int bj = 0; bj < 2; ++bj)
; #pragma unroll
;                 for (int n = 0; n < 2; ++n) swv[bj][n] = *(const f32x4*)(swp + bj * HALF + 4 * n); }
; #pragma unroll
;         for (int ai = 0; ai < 2; ++ai)
; #pragma unroll
;             for (int m = 0; m < 4; ++m) { const int row = row0 + ai * HALF + m * 16; bf16_t* rowp = base + (size_t)row * ldc + col0;
;                 float inv = 1.f;
;                 if (ss) { const f32x4* sp = (const f32x4*)(ss + (size_t)row * 32 + fq * 8); const f32x4 p0 = sp[0], p1 = sp[1];
;                     float s = ((p0[0] + p0[1]) + (p0[2] + p0[3])) + ((p1[0] + p1[1]) + (p1[2] + p1[3]));
;                     s += __shfl_xor(s, 16); s += __shfl_xor(s, 32); inv = 1.0f / sqrtf(s * (1.f / 2048.f) + 1e-6f); }
;                 f32x4 va[2][2];
; #pragma unroll
;                 for (int bj = 0; bj < 2; ++bj) { f32x4 v0 = acc[ai][bj][m][0], v1 = acc[ai][bj][m][1];
;                     if (ss) { v0 = v0 * inv + swv[bj][0]; v1 = v1 * inv + swv[bj][1]; }
;                     if (ACT == 2) { v0 = __builtin_elementwise_max(v0, (f32x4){0.f, 0.f, 0.f, 0.f}); v1 = __builtin_elementwise_max(v1, (f32x4){0.f, 0.f, 0.f, 0.f}); v0 = v0 * v0; v1 = v1 * v1; }
;                     v0 = v0 * sc; v1 = v1 * sc;
;                     if (do_nrm) { float s2 = ((v0[0] * v0[0] + v0[1] * v0[1]) + (v0[2] * v0[2] + v0[3] * v0[3])) + ((v1[0] * v1[0] + v1[1] * v1[1]) + (v1[2] * v1[2] + v1[3] * v1[3]));
;                         s2 += __shfl_xor(s2, 16); s2 += __shfl_xor(s2, 32);
;                         if (fq == 0) nrm[((size_t)(((u.pn >> 3) * 4 + (row >> 12)) * 16 + (u.pn & 7) * 2 + bj) * 4096 + (row & 4095)) * 4 + wc] = s2; }
;                     va[bj][0] = v0; va[bj][1] = v1; }
;                 if (cu_out != nullptr && u.pn >= cu_from) {
;                     const f32x4 p0 = va[0][0] * va[1][0], p1 = va[0][1] * va[1][1];
;                     u32x4 w; w.x = cvt_pk_bf16(p0[0], p0[1]); w.y = cvt_pk_bf16(p0[2], p0[3]); w.z = cvt_pk_bf16(p1[0], p1[1]); w.w = cvt_pk_bf16(p1[2], p1[3]);
.LBB0_58:
	v_lshl_add_u32 v158, s63, 8, v162
	v_ashrrev_i32_e32 v159, 31, v158
	v_lshlrev_b64 v[64:65], 7, v[158:159]
	v_lshl_add_u64 v[64:65], v[150:151], 0, v[64:65]
	global_load_dwordx4 v[168:171], v[64:65], off
	global_load_dwordx4 v[172:175], v[64:65], off offset:16
	s_ashr_i32 s25, s63, 31
	s_lshr_b32 s25, s25, 28
	s_add_i32 s25, s63, s25
	s_ashr_i32 s42, s25, 4
	s_ashr_i32 s43, s42, 31
	s_lshl_b32 s28, s64, 8
	s_lshl_b64 s[42:43], s[42:43], 15
	s_add_u32 s25, s49, s42
	s_addc_u32 s27, s54, s43
	s_ashr_i32 s29, s28, 31
	s_lshl_b64 s[42:43], s[28:29], 2
	s_add_u32 s25, s25, s42
	s_addc_u32 s27, s27, s43
	s_add_u32 s42, s25, s62
	s_addc_u32 s43, s27, 0
	global_load_dwordx4 v[76:79], v166, s[42:43]
	global_load_dwordx4 v[72:75], v166, s[42:43] offset:16
	global_load_dwordx4 v[68:71], v166, s[42:43] offset:512
	global_load_dwordx4 v[64:67], v166, s[42:43] offset:528
	v_cmp_lt_i32_e32 vcc, v232, v220
	v_readlane_b32 s72, v255, 9
	v_readlane_b32 s73, v255, 10
	v_cndmask_b32_e32 v156, v217, v232, vcc
	v_lshlrev_b32_e32 v167, 2, v156
	v_cmp_lt_i32_e32 vcc, v226, v220
	s_waitcnt vmcnt(0)
	v_mov_b32_e32 v156, v168
	v_mov_b32_e32 v157, v172
	v_mov_b32_e32 v172, v169
	v_mov_b32_e32 v160, v170
	v_mov_b32_e32 v161, v174
	v_mov_b32_e32 v174, v171
	v_pk_add_f32 v[156:157], v[156:157], v[172:173]
	v_pk_add_f32 v[160:161], v[160:161], v[174:175]
	v_lshlrev_b64 v[170:171], 14, v[158:159]
	v_pk_add_f32 v[156:157], v[156:157], v[160:161]
	v_cndmask_b32_e32 v161, v217, v226, vcc
	v_add_f32_e32 v157, v156, v157
	ds_bpermute_b32 v160, v167, v157
	v_lshlrev_b32_e32 v168, 2, v161
	v_or_b32_e32 v156, s28, v164
	s_waitcnt lgkmcnt(0)
	v_add_f32_e32 v169, v157, v160
	ds_bpermute_b32 v172, v168, v169
	v_or_b32_e32 v160, 16, v158
	v_ashrrev_i32_e32 v157, 31, v156
	v_ashrrev_i32_e32 v161, 31, v160
	v_lshl_add_u64 v[156:157], v[156:157], 1, s[16:17]
	s_waitcnt lgkmcnt(0)
	v_add_f32_e32 v159, v169, v172
	v_fmamk_f32 v159, v159, 0x3a000000, v215
	v_mul_f32_e32 v169, 0x4f800000, v159
	v_cmp_gt_f32_e32 vcc, s5, v159
	v_lshlrev_b64 v[172:173], 7, v[160:161]
	v_lshl_add_u64 v[170:171], v[156:157], 0, v[170:171]
	v_cndmask_b32_e32 v159, v159, v169, vcc
	v_sqrt_f32_e32 v169, v159
	v_lshl_add_u64 v[172:173], v[150:151], 0, v[172:173]
	v_add_u32_e32 v174, -1, v169
	v_add_u32_e32 v175, 1, v169
	v_fma_f32 v176, -v174, v169, v159
	v_fma_f32 v177, -v175, v169, v159
	v_cmp_ge_f32_e64 s[42:43], 0, v176
	s_nop 1
	v_cndmask_b32_e64 v169, v169, v174, s[42:43]
	v_cmp_lt_f32_e64 s[42:43], 0, v177
	s_nop 1
	v_cndmask_b32_e64 v169, v169, v175, s[42:43]
	v_mul_f32_e32 v174, 0x37800000, v169
	v_cndmask_b32_e32 v169, v169, v174, vcc
	v_cmp_class_f32_e32 vcc, v159, v216
	s_nop 1
	v_cndmask_b32_e32 v159, v169, v159, vcc
	v_div_scale_f32 v169, s[28:29], v159, v159, 1.0
	v_rcp_f32_e32 v174, v169
	v_div_scale_f32 v175, vcc, 1.0, v159, 1.0
	v_fma_f32 v176, -v169, v174, 1.0
	v_fmac_f32_e32 v174, v176, v174
	v_mul_f32_e32 v176, v175, v174
	v_fma_f32 v177, -v169, v176, v175
	v_fmac_f32_e32 v176, v177, v174
	v_fma_f32 v169, -v169, v176, v175
	v_div_fmas_f32 v169, v169, v174, v176
	v_div_fixup_f32 v174, v169, v159, 1.0
	v_pk_fma_f32 v[142:143], v[142:143], v[174:175], v[78:79] op_sel_hi:[1,0,1]
	v_pk_fma_f32 v[140:141], v[140:141], v[174:175], v[76:77] op_sel_hi:[1,0,1]
	v_pk_fma_f32 v[138:139], v[138:139], v[174:175], v[74:75] op_sel_hi:[1,0,1]
	v_pk_fma_f32 v[136:137], v[136:137], v[174:175], v[72:73] op_sel_hi:[1,0,1]
	v_pk_fma_f32 v[130:131], v[130:131], v[174:175], v[66:67] op_sel_hi:[1,0,1]
	v_pk_fma_f32 v[128:129], v[128:129], v[174:175], v[64:65] op_sel_hi:[1,0,1]
	v_pk_fma_f32 v[134:135], v[134:135], v[174:175], v[70:71] op_sel_hi:[1,0,1]
	v_pk_fma_f32 v[132:133], v[132:133], v[174:175], v[68:69] op_sel_hi:[1,0,1]
	v_max_f32_e32 v141, 0, v141
	v_max_f32_e32 v140, 0, v140
	v_max_f32_e32 v143, 0, v143
	v_max_f32_e32 v142, 0, v142
	v_max_f32_e32 v137, 0, v137
	v_max_f32_e32 v136, 0, v136
	v_max_f32_e32 v139, 0, v139
	v_max_f32_e32 v138, 0, v138
	v_max_f32_e32 v129, 0, v129
	v_max_f32_e32 v128, 0, v128
	v_max_f32_e32 v131, 0, v131
	v_max_f32_e32 v130, 0, v130
	v_max_f32_e32 v133, 0, v133
	v_max_f32_e32 v132, 0, v132
	v_max_f32_e32 v135, 0, v135
	v_max_f32_e32 v134, 0, v134
	v_pk_mul_f32 v[142:143], v[142:143], v[142:143]
	v_pk_mul_f32 v[140:141], v[140:141], v[140:141]
	v_pk_mul_f32 v[138:139], v[138:139], v[138:139]
	v_pk_mul_f32 v[136:137], v[136:137], v[136:137]
	v_pk_mul_f32 v[174:175], v[130:131], v[130:131]
	v_pk_mul_f32 v[176:177], v[128:129], v[128:129]
	v_cvt_pk_bf16_f32 v128, v140, v141
	v_cvt_pk_bf16_f32 v129, v142, v143
	v_cvt_pk_bf16_f32 v130, v136, v137
	v_cvt_pk_bf16_f32 v131, v138, v139
	v_pk_mul_f32 v[134:135], v[134:135], v[134:135]
	v_pk_mul_f32 v[132:133], v[132:133], v[132:133]
	global_store_dwordx4 v[170:171], v[128:131], off
	s_nop 1
	v_cvt_pk_bf16_f32 v128, v132, v133
	v_cvt_pk_bf16_f32 v129, v134, v135
	v_cvt_pk_bf16_f32 v130, v176, v177
	v_cvt_pk_bf16_f32 v131, v174, v175
	global_store_dwordx4 v[170:171], v[128:131], off offset:256
	global_load_dwordx4 v[128:131], v[172:173], off
	s_nop 0
	global_load_dwordx4 v[132:135], v[172:173], off offset:16
	s_waitcnt vmcnt(1)
	v_mov_b32_e32 v136, v128
	s_waitcnt vmcnt(0)
	v_mov_b32_e32 v137, v132
	v_mov_b32_e32 v132, v129
	v_mov_b32_e32 v128, v130
	v_mov_b32_e32 v129, v134
	v_mov_b32_e32 v134, v131
	v_pk_add_f32 v[130:131], v[136:137], v[132:133]
	v_pk_add_f32 v[128:129], v[128:129], v[134:135]
	s_nop 0
	v_pk_add_f32 v[128:129], v[130:131], v[128:129]
	s_nop 0
	v_add_f32_e32 v128, v128, v129
	ds_bpermute_b32 v129, v167, v128
	s_waitcnt lgkmcnt(0)
;     __device__ __forceinline__ void operator()(const f32x4 (&acc)[2][2][4][2], const Unit& u, int wr, int wc, int fr, int fq) const {
;     ...
;             for (int m = 0; m < 4; ++m) { const int row = row0 + ai * HALF + m * 16; bf16_t* rowp = base + (size_t)row * ldc + col0;
;                 float inv = 1.f;
;                 if (ss) { const f32x4* sp = (const f32x4*)(ss + (size_t)row * 32 + fq * 8); const f32x4 p0 = sp[0], p1 = sp[1];
;                     float s = ((p0[0] + p0[1]) + (p0[2] + p0[3])) + ((p1[0] + p1[1]) + (p1[2] + p1[3]));
;                     s += __shfl_xor(s, 16); s += __shfl_xor(s, 32); inv = 1.0f / sqrtf(s * (1.f / 2048.f) + 1e-6f); }
;                 f32x4 va[2][2];
; #pragma unroll
;                 for (int bj = 0; bj < 2; ++bj) { f32x4 v0 = acc[ai][bj][m][0], v1 = acc[ai][bj][m][1];
;                     if (ss) { v0 = v0 * inv + swv[bj][0]; v1 = v1 * inv + swv[bj][1]; }
;                     if (ACT == 2) { v0 = __builtin_elementwise_max(v0, (f32x4){0.f, 0.f, 0.f, 0.f}); v1 = __builtin_elementwise_max(v1, (f32x4){0.f, 0.f, 0.f, 0.f}); v0 = v0 * v0; v1 = v1 * v1; }
;                     v0 = v0 * sc; v1 = v1 * sc;
;                     if (do_nrm) { float s2 = ((v0[0] * v0[0] + v0[1] * v0[1]) + (v0[2] * v0[2] + v0[3] * v0[3])) + ((v1[0] * v1[0] + v1[1] * v1[1]) + (v1[2] * v1[2] + v1[3] * v1[3]));
;                         s2 += __shfl_xor(s2, 16); s2 += __shfl_xor(s2, 32);
;                         if (fq == 0) nrm[((size_t)(((u.pn >> 3) * 4 + (row >> 12)) * 16 + (u.pn & 7) * 2 + bj) * 4096 + (row & 4095)) * 4 + wc] = s2; }
;                     va[bj][0] = v0; va[bj][1] = v1; }
;                 if (cu_out != nullptr && u.pn >= cu_from) {
;                     const f32x4 p0 = va[0][0] * va[1][0], p1 = va[0][1] * va[1][1];
;                     u32x4 w; w.x = cvt_pk_bf16(p0[0], p0[1]); w.y = cvt_pk_bf16(p0[2], p0[3]); w.z = cvt_pk_bf16(p1[0], p1[1]); w.w = cvt_pk_bf16(p1[2], p1[3]);
;                     *(u32x4*)(cu_out + (size_t)row * ldc + (u.pn - cu_from) * HALF + wc * 32 + 8 * fq) = w;
;                 } else {
; #pragma unroll
;                     for (int bj = 0; bj < 2; ++bj) { const f32x4 v0 = va[bj][0], v1 = va[bj][1];
;                         u32x4 w; w.x = cvt_pk_bf16(v0[0], v0[1]); w.y = cvt_pk_bf16(v0[2], v0[3]); w.z = cvt_pk_bf16(v1[0], v1[1]); w.w = cvt_pk_bf16(v1[2], v1[3]);
	v_add_f32_e32 v130, v128, v129
	ds_bpermute_b32 v131, v168, v130
	v_or_b32_e32 v128, 32, v158
	v_ashrrev_i32_e32 v129, 31, v128
	v_lshlrev_b64 v[132:133], 7, v[128:129]
	v_lshl_add_u64 v[132:133], v[150:151], 0, v[132:133]
	s_waitcnt lgkmcnt(0)
	v_add_f32_e32 v130, v130, v131
	v_fmamk_f32 v130, v130, 0x3a000000, v215
	v_mul_f32_e32 v131, 0x4f800000, v130
	v_cmp_gt_f32_e32 vcc, s5, v130
	s_nop 1
	v_cndmask_b32_e32 v134, v130, v131, vcc
	v_sqrt_f32_e32 v135, v134
	v_lshlrev_b64 v[130:131], 14, v[160:161]
	v_lshl_add_u64 v[130:131], v[156:157], 0, v[130:131]
	v_add_u32_e32 v136, -1, v135
	v_add_u32_e32 v137, 1, v135
	v_fma_f32 v138, -v136, v135, v134
	v_fma_f32 v139, -v137, v135, v134
	v_cmp_ge_f32_e64 s[42:43], 0, v138
	s_nop 1
	v_cndmask_b32_e64 v135, v135, v136, s[42:43]
	v_cmp_lt_f32_e64 s[42:43], 0, v139
	s_nop 1
	v_cndmask_b32_e64 v135, v135, v137, s[42:43]
	v_mul_f32_e32 v136, 0x37800000, v135
	v_cndmask_b32_e32 v135, v135, v136, vcc
	v_cmp_class_f32_e32 vcc, v134, v216
	s_nop 1
	v_cndmask_b32_e32 v134, v135, v134, vcc
	v_div_scale_f32 v135, s[28:29], v134, v134, 1.0
	v_rcp_f32_e32 v136, v135
	v_div_scale_f32 v137, vcc, 1.0, v134, 1.0
	v_fma_f32 v138, -v135, v136, 1.0
	v_fmac_f32_e32 v136, v138, v136
	v_mul_f32_e32 v138, v137, v136
	v_fma_f32 v139, -v135, v138, v137
	v_fmac_f32_e32 v138, v139, v136
	v_fma_f32 v135, -v135, v138, v137
	v_div_fmas_f32 v135, v135, v136, v138
	v_div_fixup_f32 v134, v135, v134, 1.0
	v_pk_fma_f32 v[126:127], v[126:127], v[134:135], v[78:79] op_sel_hi:[1,0,1]
	v_pk_fma_f32 v[124:125], v[124:125], v[134:135], v[76:77] op_sel_hi:[1,0,1]
	v_pk_fma_f32 v[122:123], v[122:123], v[134:135], v[74:75] op_sel_hi:[1,0,1]
	v_pk_fma_f32 v[120:121], v[120:121], v[134:135], v[72:73] op_sel_hi:[1,0,1]
	v_pk_fma_f32 v[114:115], v[114:115], v[134:135], v[66:67] op_sel_hi:[1,0,1]
	v_pk_fma_f32 v[112:113], v[112:113], v[134:135], v[64:65] op_sel_hi:[1,0,1]
	v_pk_fma_f32 v[118:119], v[118:119], v[134:135], v[70:71] op_sel_hi:[1,0,1]
	v_pk_fma_f32 v[116:117], v[116:117], v[134:135], v[68:69] op_sel_hi:[1,0,1]
	v_max_f32_e32 v125, 0, v125
	v_max_f32_e32 v124, 0, v124
	v_max_f32_e32 v127, 0, v127
	v_max_f32_e32 v126, 0, v126
	v_max_f32_e32 v121, 0, v121
	v_max_f32_e32 v120, 0, v120
	v_max_f32_e32 v123, 0, v123
	v_max_f32_e32 v122, 0, v122
	v_max_f32_e32 v113, 0, v113
	v_max_f32_e32 v112, 0, v112
	v_max_f32_e32 v115, 0, v115
	v_max_f32_e32 v114, 0, v114
	v_max_f32_e32 v117, 0, v117
	v_max_f32_e32 v116, 0, v116
	v_max_f32_e32 v119, 0, v119
	v_max_f32_e32 v118, 0, v118
	v_pk_mul_f32 v[126:127], v[126:127], v[126:127]
	v_pk_mul_f32 v[124:125], v[124:125], v[124:125]
	v_pk_mul_f32 v[122:123], v[122:123], v[122:123]
	v_pk_mul_f32 v[120:121], v[120:121], v[120:121]
	v_pk_mul_f32 v[134:135], v[114:115], v[114:115]
	v_pk_mul_f32 v[136:137], v[112:113], v[112:113]
	v_cvt_pk_bf16_f32 v112, v124, v125
	v_cvt_pk_bf16_f32 v113, v126, v127
	v_cvt_pk_bf16_f32 v114, v120, v121
	v_cvt_pk_bf16_f32 v115, v122, v123
	v_pk_mul_f32 v[118:119], v[118:119], v[118:119]
	v_pk_mul_f32 v[116:117], v[116:117], v[116:117]
	global_store_dwordx4 v[130:131], v[112:115], off
	s_nop 1
	v_cvt_pk_bf16_f32 v112, v116, v117
	v_cvt_pk_bf16_f32 v113, v118, v119
	v_cvt_pk_bf16_f32 v114, v136, v137
	v_cvt_pk_bf16_f32 v115, v134, v135
	global_store_dwordx4 v[130:131], v[112:115], off offset:256
	global_load_dwordx4 v[112:115], v[132:133], off
	s_nop 0
	global_load_dwordx4 v[116:119], v[132:133], off offset:16
	s_waitcnt vmcnt(1)
	v_mov_b32_e32 v120, v112
	s_waitcnt vmcnt(0)
	v_mov_b32_e32 v121, v116
	v_mov_b32_e32 v116, v113
	v_mov_b32_e32 v112, v114
	v_mov_b32_e32 v113, v118
	v_mov_b32_e32 v118, v115
	v_pk_add_f32 v[114:115], v[120:121], v[116:117]
	v_pk_add_f32 v[112:113], v[112:113], v[118:119]
	s_nop 0
	v_pk_add_f32 v[112:113], v[114:115], v[112:113]
	s_nop 0
	v_add_f32_e32 v112, v112, v113
	ds_bpermute_b32 v113, v167, v112
	s_waitcnt lgkmcnt(0)
	v_add_f32_e32 v114, v112, v113
	ds_bpermute_b32 v115, v168, v114
	v_or_b32_e32 v112, 48, v158
	v_ashrrev_i32_e32 v113, 31, v112
	v_lshlrev_b64 v[116:117], 7, v[112:113]
	v_lshl_add_u64 v[116:117], v[150:151], 0, v[116:117]
	s_waitcnt lgkmcnt(0)
	v_add_f32_e32 v114, v114, v115
	v_fmamk_f32 v114, v114, 0x3a000000, v215
	v_mul_f32_e32 v115, 0x4f800000, v114
	v_cmp_gt_f32_e32 vcc, s5, v114
	s_nop 1
	v_cndmask_b32_e32 v118, v114, v115, vcc
	v_sqrt_f32_e32 v119, v118
	v_lshlrev_b64 v[114:115], 14, v[128:129]
	v_lshl_add_u64 v[114:115], v[156:157], 0, v[114:115]
	v_add_u32_e32 v120, -1, v119
	v_add_u32_e32 v121, 1, v119
	v_fma_f32 v122, -v120, v119, v118
	v_fma_f32 v123, -v121, v119, v118
	v_cmp_ge_f32_e64 s[42:43], 0, v122
	s_nop 1
	v_cndmask_b32_e64 v119, v119, v120, s[42:43]
	v_cmp_lt_f32_e64 s[42:43], 0, v123
	s_nop 1
	v_cndmask_b32_e64 v119, v119, v121, s[42:43]
	v_mul_f32_e32 v120, 0x37800000, v119
	v_cndmask_b32_e32 v119, v119, v120, vcc
	v_cmp_class_f32_e32 vcc, v118, v216
	s_nop 1
	v_cndmask_b32_e32 v118, v119, v118, vcc
	v_div_scale_f32 v119, s[28:29], v118, v118, 1.0
	v_rcp_f32_e32 v120, v119
	v_div_scale_f32 v121, vcc, 1.0, v118, 1.0
	v_fma_f32 v122, -v119, v120, 1.0
	v_fmac_f32_e32 v120, v122, v120
	v_mul_f32_e32 v122, v121, v120
	v_fma_f32 v123, -v119, v122, v121
	v_fmac_f32_e32 v122, v123, v120
	v_fma_f32 v119, -v119, v122, v121
	v_div_fmas_f32 v119, v119, v120, v122
	v_div_fixup_f32 v118, v119, v118, 1.0
	v_pk_fma_f32 v[110:111], v[110:111], v[118:119], v[78:79] op_sel_hi:[1,0,1]
	v_pk_fma_f32 v[108:109], v[108:109], v[118:119], v[76:77] op_sel_hi:[1,0,1]
	v_pk_fma_f32 v[106:107], v[106:107], v[118:119], v[74:75] op_sel_hi:[1,0,1]
	v_pk_fma_f32 v[104:105], v[104:105], v[118:119], v[72:73] op_sel_hi:[1,0,1]
;     __device__ __forceinline__ void operator()(const f32x4 (&acc)[2][2][4][2], const Unit& u, int wr, int wc, int fr, int fq) const {
;     ...
;             for (int m = 0; m < 4; ++m) { const int row = row0 + ai * HALF + m * 16; bf16_t* rowp = base + (size_t)row * ldc + col0;
;                 float inv = 1.f;
;                 if (ss) { const f32x4* sp = (const f32x4*)(ss + (size_t)row * 32 + fq * 8); const f32x4 p0 = sp[0], p1 = sp[1];
;                     float s = ((p0[0] + p0[1]) + (p0[2] + p0[3])) + ((p1[0] + p1[1]) + (p1[2] + p1[3]));
;                     s += __shfl_xor(s, 16); s += __shfl_xor(s, 32); inv = 1.0f / sqrtf(s * (1.f / 2048.f) + 1e-6f); }
;                 f32x4 va[2][2];
; #pragma unroll
;                 for (int bj = 0; bj < 2; ++bj) { f32x4 v0 = acc[ai][bj][m][0], v1 = acc[ai][bj][m][1];
;                     if (ss) { v0 = v0 * inv + swv[bj][0]; v1 = v1 * inv + swv[bj][1]; }
;                     if (ACT == 2) { v0 = __builtin_elementwise_max(v0, (f32x4){0.f, 0.f, 0.f, 0.f}); v1 = __builtin_elementwise_max(v1, (f32x4){0.f, 0.f, 0.f, 0.f}); v0 = v0 * v0; v1 = v1 * v1; }
;                     v0 = v0 * sc; v1 = v1 * sc;
;                     if (do_nrm) { float s2 = ((v0[0] * v0[0] + v0[1] * v0[1]) + (v0[2] * v0[2] + v0[3] * v0[3])) + ((v1[0] * v1[0] + v1[1] * v1[1]) + (v1[2] * v1[2] + v1[3] * v1[3]));
;                         s2 += __shfl_xor(s2, 16); s2 += __shfl_xor(s2, 32);
;                         if (fq == 0) nrm[((size_t)(((u.pn >> 3) * 4 + (row >> 12)) * 16 + (u.pn & 7) * 2 + bj) * 4096 + (row & 4095)) * 4 + wc] = s2; }
;                     va[bj][0] = v0; va[bj][1] = v1; }
;                 if (cu_out != nullptr && u.pn >= cu_from) {
;                     const f32x4 p0 = va[0][0] * va[1][0], p1 = va[0][1] * va[1][1];
;                     u32x4 w; w.x = cvt_pk_bf16(p0[0], p0[1]); w.y = cvt_pk_bf16(p0[2], p0[3]); w.z = cvt_pk_bf16(p1[0], p1[1]); w.w = cvt_pk_bf16(p1[2], p1[3]);
;                     *(u32x4*)(cu_out + (size_t)row * ldc + (u.pn - cu_from) * HALF + wc * 32 + 8 * fq) = w;
;                 } else {
; #pragma unroll
;                     for (int bj = 0; bj < 2; ++bj) { const f32x4 v0 = va[bj][0], v1 = va[bj][1];
;                         u32x4 w; w.x = cvt_pk_bf16(v0[0], v0[1]); w.y = cvt_pk_bf16(v0[2], v0[3]); w.z = cvt_pk_bf16(v1[0], v1[1]); w.w = cvt_pk_bf16(v1[2], v1[3]);
	v_pk_fma_f32 v[98:99], v[98:99], v[118:119], v[66:67] op_sel_hi:[1,0,1]
	v_pk_fma_f32 v[96:97], v[96:97], v[118:119], v[64:65] op_sel_hi:[1,0,1]
	v_pk_fma_f32 v[102:103], v[102:103], v[118:119], v[70:71] op_sel_hi:[1,0,1]
	v_pk_fma_f32 v[100:101], v[100:101], v[118:119], v[68:69] op_sel_hi:[1,0,1]
	v_max_f32_e32 v109, 0, v109
	v_max_f32_e32 v108, 0, v108
	v_max_f32_e32 v111, 0, v111
	v_max_f32_e32 v110, 0, v110
	v_max_f32_e32 v105, 0, v105
	v_max_f32_e32 v104, 0, v104
	v_max_f32_e32 v107, 0, v107
	v_max_f32_e32 v106, 0, v106
	v_max_f32_e32 v97, 0, v97
	v_max_f32_e32 v96, 0, v96
	v_max_f32_e32 v99, 0, v99
	v_max_f32_e32 v98, 0, v98
	v_max_f32_e32 v101, 0, v101
	v_max_f32_e32 v100, 0, v100
	v_max_f32_e32 v103, 0, v103
	v_max_f32_e32 v102, 0, v102
	v_pk_mul_f32 v[110:111], v[110:111], v[110:111]
	v_pk_mul_f32 v[108:109], v[108:109], v[108:109]
	v_pk_mul_f32 v[106:107], v[106:107], v[106:107]
	v_pk_mul_f32 v[104:105], v[104:105], v[104:105]
	v_pk_mul_f32 v[118:119], v[98:99], v[98:99]
	v_pk_mul_f32 v[120:121], v[96:97], v[96:97]
	v_cvt_pk_bf16_f32 v96, v108, v109
	v_cvt_pk_bf16_f32 v97, v110, v111
	v_cvt_pk_bf16_f32 v98, v104, v105
	v_cvt_pk_bf16_f32 v99, v106, v107
	v_pk_mul_f32 v[102:103], v[102:103], v[102:103]
	v_pk_mul_f32 v[100:101], v[100:101], v[100:101]
	global_store_dwordx4 v[114:115], v[96:99], off
	s_nop 1
	v_cvt_pk_bf16_f32 v96, v100, v101
	v_cvt_pk_bf16_f32 v97, v102, v103
	v_cvt_pk_bf16_f32 v98, v120, v121
	v_cvt_pk_bf16_f32 v99, v118, v119
	global_store_dwordx4 v[114:115], v[96:99], off offset:256
	global_load_dwordx4 v[96:99], v[116:117], off
	s_nop 0
	global_load_dwordx4 v[100:103], v[116:117], off offset:16
	s_waitcnt vmcnt(1)
	v_mov_b32_e32 v104, v96
	s_waitcnt vmcnt(0)
	v_mov_b32_e32 v105, v100
	v_mov_b32_e32 v100, v97
	v_mov_b32_e32 v96, v98
	v_mov_b32_e32 v97, v102
	v_mov_b32_e32 v102, v99
	v_pk_add_f32 v[98:99], v[104:105], v[100:101]
	v_pk_add_f32 v[96:97], v[96:97], v[102:103]
	s_nop 0
	v_pk_add_f32 v[96:97], v[98:99], v[96:97]
	s_nop 0
	v_add_f32_e32 v96, v96, v97
	ds_bpermute_b32 v97, v167, v96
	s_waitcnt lgkmcnt(0)
	v_add_f32_e32 v98, v96, v97
	ds_bpermute_b32 v99, v168, v98
	v_add_u32_e32 v96, 0x80, v158
	v_ashrrev_i32_e32 v97, 31, v96
	v_lshlrev_b64 v[100:101], 7, v[96:97]
	v_lshl_add_u64 v[100:101], v[150:151], 0, v[100:101]
	s_waitcnt lgkmcnt(0)
	v_add_f32_e32 v98, v98, v99
	v_fmamk_f32 v98, v98, 0x3a000000, v215
	v_mul_f32_e32 v99, 0x4f800000, v98
	v_cmp_gt_f32_e32 vcc, s5, v98
	s_nop 1
	v_cndmask_b32_e32 v102, v98, v99, vcc
	v_sqrt_f32_e32 v103, v102
	v_lshlrev_b64 v[98:99], 14, v[112:113]
	v_lshl_add_u64 v[98:99], v[156:157], 0, v[98:99]
	v_add_u32_e32 v104, -1, v103
	v_add_u32_e32 v105, 1, v103
	v_fma_f32 v106, -v104, v103, v102
	v_fma_f32 v107, -v105, v103, v102
	v_cmp_ge_f32_e64 s[42:43], 0, v106
	s_nop 1
	v_cndmask_b32_e64 v103, v103, v104, s[42:43]
	v_cmp_lt_f32_e64 s[42:43], 0, v107
	s_nop 1
	v_cndmask_b32_e64 v103, v103, v105, s[42:43]
	v_mul_f32_e32 v104, 0x37800000, v103
	v_cndmask_b32_e32 v103, v103, v104, vcc
	v_cmp_class_f32_e32 vcc, v102, v216
	s_nop 1
	v_cndmask_b32_e32 v102, v103, v102, vcc
	v_div_scale_f32 v103, s[28:29], v102, v102, 1.0
	v_rcp_f32_e32 v104, v103
	v_div_scale_f32 v105, vcc, 1.0, v102, 1.0
	v_fma_f32 v106, -v103, v104, 1.0
	v_fmac_f32_e32 v104, v106, v104
	v_mul_f32_e32 v106, v105, v104
	v_fma_f32 v107, -v103, v106, v105
	v_fmac_f32_e32 v106, v107, v104
	v_fma_f32 v103, -v103, v106, v105
	v_div_fmas_f32 v103, v103, v104, v106
	v_div_fixup_f32 v102, v103, v102, 1.0
	v_pk_fma_f32 v[94:95], v[94:95], v[102:103], v[78:79] op_sel_hi:[1,0,1]
	v_pk_fma_f32 v[92:93], v[92:93], v[102:103], v[76:77] op_sel_hi:[1,0,1]
	v_pk_fma_f32 v[90:91], v[90:91], v[102:103], v[74:75] op_sel_hi:[1,0,1]
	v_pk_fma_f32 v[88:89], v[88:89], v[102:103], v[72:73] op_sel_hi:[1,0,1]
	v_pk_fma_f32 v[82:83], v[82:83], v[102:103], v[66:67] op_sel_hi:[1,0,1]
	v_pk_fma_f32 v[80:81], v[80:81], v[102:103], v[64:65] op_sel_hi:[1,0,1]
	v_pk_fma_f32 v[86:87], v[86:87], v[102:103], v[70:71] op_sel_hi:[1,0,1]
	v_pk_fma_f32 v[84:85], v[84:85], v[102:103], v[68:69] op_sel_hi:[1,0,1]
	v_max_f32_e32 v93, 0, v93
	v_max_f32_e32 v92, 0, v92
	v_max_f32_e32 v95, 0, v95
	v_max_f32_e32 v94, 0, v94
	v_max_f32_e32 v89, 0, v89
	v_max_f32_e32 v88, 0, v88
	v_max_f32_e32 v91, 0, v91
	v_max_f32_e32 v90, 0, v90
	v_max_f32_e32 v81, 0, v81
	v_max_f32_e32 v80, 0, v80
	v_max_f32_e32 v83, 0, v83
	v_max_f32_e32 v82, 0, v82
	v_max_f32_e32 v85, 0, v85
	v_max_f32_e32 v84, 0, v84
	v_max_f32_e32 v87, 0, v87
	v_max_f32_e32 v86, 0, v86
	v_pk_mul_f32 v[94:95], v[94:95], v[94:95]
	v_pk_mul_f32 v[92:93], v[92:93], v[92:93]
	v_pk_mul_f32 v[90:91], v[90:91], v[90:91]
	v_pk_mul_f32 v[88:89], v[88:89], v[88:89]
	v_pk_mul_f32 v[102:103], v[82:83], v[82:83]
	v_pk_mul_f32 v[104:105], v[80:81], v[80:81]
	v_cvt_pk_bf16_f32 v80, v92, v93
	v_cvt_pk_bf16_f32 v81, v94, v95
	v_cvt_pk_bf16_f32 v82, v88, v89
	v_cvt_pk_bf16_f32 v83, v90, v91
	v_pk_mul_f32 v[86:87], v[86:87], v[86:87]
	v_pk_mul_f32 v[84:85], v[84:85], v[84:85]
	global_store_dwordx4 v[98:99], v[80:83], off
	s_nop 1
	v_cvt_pk_bf16_f32 v80, v84, v85
	v_cvt_pk_bf16_f32 v81, v86, v87
	v_cvt_pk_bf16_f32 v82, v104, v105
	v_cvt_pk_bf16_f32 v83, v102, v103
	global_store_dwordx4 v[98:99], v[80:83], off offset:256
	global_load_dwordx4 v[80:83], v[100:101], off
	s_nop 0
	global_load_dwordx4 v[84:87], v[100:101], off offset:16
	s_waitcnt vmcnt(1)
	v_mov_b32_e32 v88, v80
	s_waitcnt vmcnt(0)
	v_mov_b32_e32 v89, v84
	v_mov_b32_e32 v84, v81
	v_mov_b32_e32 v80, v82
	v_mov_b32_e32 v81, v86
	v_mov_b32_e32 v86, v83
	v_pk_add_f32 v[82:83], v[88:89], v[84:85]
	v_pk_add_f32 v[80:81], v[80:81], v[86:87]
	s_nop 0
	v_pk_add_f32 v[80:81], v[82:83], v[80:81]
	s_nop 0
	v_add_f32_e32 v80, v80, v81
	ds_bpermute_b32 v81, v167, v80
	s_waitcnt lgkmcnt(0)
;     __device__ __forceinline__ void operator()(const f32x4 (&acc)[2][2][4][2], const Unit& u, int wr, int wc, int fr, int fq) const {
;     ...
;             for (int m = 0; m < 4; ++m) { const int row = row0 + ai * HALF + m * 16; bf16_t* rowp = base + (size_t)row * ldc + col0;
;                 float inv = 1.f;
;                 if (ss) { const f32x4* sp = (const f32x4*)(ss + (size_t)row * 32 + fq * 8); const f32x4 p0 = sp[0], p1 = sp[1];
;                     float s = ((p0[0] + p0[1]) + (p0[2] + p0[3])) + ((p1[0] + p1[1]) + (p1[2] + p1[3]));
;                     s += __shfl_xor(s, 16); s += __shfl_xor(s, 32); inv = 1.0f / sqrtf(s * (1.f / 2048.f) + 1e-6f); }
;                 f32x4 va[2][2];
; #pragma unroll
;                 for (int bj = 0; bj < 2; ++bj) { f32x4 v0 = acc[ai][bj][m][0], v1 = acc[ai][bj][m][1];
;                     if (ss) { v0 = v0 * inv + swv[bj][0]; v1 = v1 * inv + swv[bj][1]; }
;                     if (ACT == 2) { v0 = __builtin_elementwise_max(v0, (f32x4){0.f, 0.f, 0.f, 0.f}); v1 = __builtin_elementwise_max(v1, (f32x4){0.f, 0.f, 0.f, 0.f}); v0 = v0 * v0; v1 = v1 * v1; }
;                     v0 = v0 * sc; v1 = v1 * sc;
;                     if (do_nrm) { float s2 = ((v0[0] * v0[0] + v0[1] * v0[1]) + (v0[2] * v0[2] + v0[3] * v0[3])) + ((v1[0] * v1[0] + v1[1] * v1[1]) + (v1[2] * v1[2] + v1[3] * v1[3]));
;                         s2 += __shfl_xor(s2, 16); s2 += __shfl_xor(s2, 32);
;                         if (fq == 0) nrm[((size_t)(((u.pn >> 3) * 4 + (row >> 12)) * 16 + (u.pn & 7) * 2 + bj) * 4096 + (row & 4095)) * 4 + wc] = s2; }
;                     va[bj][0] = v0; va[bj][1] = v1; }
;                 if (cu_out != nullptr && u.pn >= cu_from) {
;                     const f32x4 p0 = va[0][0] * va[1][0], p1 = va[0][1] * va[1][1];
;                     u32x4 w; w.x = cvt_pk_bf16(p0[0], p0[1]); w.y = cvt_pk_bf16(p0[2], p0[3]); w.z = cvt_pk_bf16(p1[0], p1[1]); w.w = cvt_pk_bf16(p1[2], p1[3]);
;                     *(u32x4*)(cu_out + (size_t)row * ldc + (u.pn - cu_from) * HALF + wc * 32 + 8 * fq) = w;
;                 } else {
; #pragma unroll
;                     for (int bj = 0; bj < 2; ++bj) { const f32x4 v0 = va[bj][0], v1 = va[bj][1];
;                         u32x4 w; w.x = cvt_pk_bf16(v0[0], v0[1]); w.y = cvt_pk_bf16(v0[2], v0[3]); w.z = cvt_pk_bf16(v1[0], v1[1]); w.w = cvt_pk_bf16(v1[2], v1[3]);
	v_add_f32_e32 v82, v80, v81
	ds_bpermute_b32 v83, v168, v82
	v_add_u32_e32 v80, 0x90, v158
	v_ashrrev_i32_e32 v81, 31, v80
	v_lshlrev_b64 v[84:85], 7, v[80:81]
	v_lshl_add_u64 v[84:85], v[150:151], 0, v[84:85]
	s_waitcnt lgkmcnt(0)
	v_add_f32_e32 v82, v82, v83
	v_fmamk_f32 v82, v82, 0x3a000000, v215
	v_mul_f32_e32 v83, 0x4f800000, v82
	v_cmp_gt_f32_e32 vcc, s5, v82
	s_nop 1
	v_cndmask_b32_e32 v86, v82, v83, vcc
	v_sqrt_f32_e32 v87, v86
	v_lshlrev_b64 v[82:83], 14, v[96:97]
	v_lshl_add_u64 v[82:83], v[156:157], 0, v[82:83]
	v_add_u32_e32 v88, -1, v87
	v_add_u32_e32 v89, 1, v87
	v_fma_f32 v90, -v88, v87, v86
	v_fma_f32 v91, -v89, v87, v86
	v_cmp_ge_f32_e64 s[42:43], 0, v90
	s_nop 1
	v_cndmask_b32_e64 v87, v87, v88, s[42:43]
	v_cmp_lt_f32_e64 s[42:43], 0, v91
	s_nop 1
	v_cndmask_b32_e64 v87, v87, v89, s[42:43]
	v_mul_f32_e32 v88, 0x37800000, v87
	v_cndmask_b32_e32 v87, v87, v88, vcc
	v_cmp_class_f32_e32 vcc, v86, v216
	s_nop 1
	v_cndmask_b32_e32 v86, v87, v86, vcc
	v_div_scale_f32 v87, s[28:29], v86, v86, 1.0
	v_rcp_f32_e32 v88, v87
	v_div_scale_f32 v89, vcc, 1.0, v86, 1.0
	v_fma_f32 v90, -v87, v88, 1.0
	v_fmac_f32_e32 v88, v90, v88
	v_mul_f32_e32 v90, v89, v88
	v_fma_f32 v91, -v87, v90, v89
	v_fmac_f32_e32 v90, v91, v88
	v_fma_f32 v87, -v87, v90, v89
	v_div_fmas_f32 v87, v87, v88, v90
	v_div_fixup_f32 v86, v87, v86, 1.0
	v_pk_fma_f32 v[62:63], v[62:63], v[86:87], v[78:79] op_sel_hi:[1,0,1]
	v_pk_fma_f32 v[60:61], v[60:61], v[86:87], v[76:77] op_sel_hi:[1,0,1]
	v_pk_fma_f32 v[58:59], v[58:59], v[86:87], v[74:75] op_sel_hi:[1,0,1]
	v_pk_fma_f32 v[56:57], v[56:57], v[86:87], v[72:73] op_sel_hi:[1,0,1]
	v_pk_fma_f32 v[50:51], v[50:51], v[86:87], v[66:67] op_sel_hi:[1,0,1]
	v_pk_fma_f32 v[48:49], v[48:49], v[86:87], v[64:65] op_sel_hi:[1,0,1]
	v_pk_fma_f32 v[54:55], v[54:55], v[86:87], v[70:71] op_sel_hi:[1,0,1]
	v_pk_fma_f32 v[52:53], v[52:53], v[86:87], v[68:69] op_sel_hi:[1,0,1]
	v_max_f32_e32 v61, 0, v61
	v_max_f32_e32 v60, 0, v60
	v_max_f32_e32 v63, 0, v63
	v_max_f32_e32 v62, 0, v62
	v_max_f32_e32 v57, 0, v57
	v_max_f32_e32 v56, 0, v56
	v_max_f32_e32 v59, 0, v59
	v_max_f32_e32 v58, 0, v58
	v_max_f32_e32 v49, 0, v49
	v_max_f32_e32 v48, 0, v48
	v_max_f32_e32 v51, 0, v51
	v_max_f32_e32 v50, 0, v50
	v_max_f32_e32 v53, 0, v53
	v_max_f32_e32 v52, 0, v52
	v_max_f32_e32 v55, 0, v55
	v_max_f32_e32 v54, 0, v54
	v_pk_mul_f32 v[62:63], v[62:63], v[62:63]
	v_pk_mul_f32 v[60:61], v[60:61], v[60:61]
	v_pk_mul_f32 v[58:59], v[58:59], v[58:59]
	v_pk_mul_f32 v[56:57], v[56:57], v[56:57]
	v_pk_mul_f32 v[86:87], v[50:51], v[50:51]
	v_pk_mul_f32 v[88:89], v[48:49], v[48:49]
	v_cvt_pk_bf16_f32 v48, v60, v61
	v_cvt_pk_bf16_f32 v49, v62, v63
	v_cvt_pk_bf16_f32 v50, v56, v57
	v_cvt_pk_bf16_f32 v51, v58, v59
	v_pk_mul_f32 v[54:55], v[54:55], v[54:55]
	v_pk_mul_f32 v[52:53], v[52:53], v[52:53]
	global_store_dwordx4 v[82:83], v[48:51], off
	s_nop 1
	v_cvt_pk_bf16_f32 v48, v52, v53
	v_cvt_pk_bf16_f32 v49, v54, v55
	v_cvt_pk_bf16_f32 v50, v88, v89
	v_cvt_pk_bf16_f32 v51, v86, v87
	global_store_dwordx4 v[82:83], v[48:51], off offset:256
	global_load_dwordx4 v[48:51], v[84:85], off
	s_nop 0
	global_load_dwordx4 v[52:55], v[84:85], off offset:16
	s_waitcnt vmcnt(1)
	v_mov_b32_e32 v56, v48
	s_waitcnt vmcnt(0)
	v_mov_b32_e32 v57, v52
	v_mov_b32_e32 v52, v49
	v_mov_b32_e32 v48, v50
	v_mov_b32_e32 v49, v54
	v_mov_b32_e32 v54, v51
	v_pk_add_f32 v[50:51], v[56:57], v[52:53]
	v_pk_add_f32 v[48:49], v[48:49], v[54:55]
	s_nop 0
	v_pk_add_f32 v[48:49], v[50:51], v[48:49]
	s_nop 0
	v_add_f32_e32 v48, v48, v49
	ds_bpermute_b32 v49, v167, v48
	s_waitcnt lgkmcnt(0)
	v_add_f32_e32 v50, v48, v49
	ds_bpermute_b32 v51, v168, v50
	v_add_u32_e32 v48, 0xa0, v158
	v_ashrrev_i32_e32 v49, 31, v48
	v_lshlrev_b64 v[52:53], 7, v[48:49]
	v_lshl_add_u64 v[52:53], v[150:151], 0, v[52:53]
	s_waitcnt lgkmcnt(0)
	v_add_f32_e32 v50, v50, v51
	v_fmamk_f32 v50, v50, 0x3a000000, v215
	v_mul_f32_e32 v51, 0x4f800000, v50
	v_cmp_gt_f32_e32 vcc, s5, v50
	s_nop 1
	v_cndmask_b32_e32 v54, v50, v51, vcc
	v_sqrt_f32_e32 v55, v54
	v_lshlrev_b64 v[50:51], 14, v[80:81]
	v_lshl_add_u64 v[50:51], v[156:157], 0, v[50:51]
	v_add_u32_e32 v56, -1, v55
	v_add_u32_e32 v57, 1, v55
	v_fma_f32 v58, -v56, v55, v54
	v_fma_f32 v59, -v57, v55, v54
	v_cmp_ge_f32_e64 s[42:43], 0, v58
	s_nop 1
	v_cndmask_b32_e64 v55, v55, v56, s[42:43]
	v_cmp_lt_f32_e64 s[42:43], 0, v59
	s_nop 1
	v_cndmask_b32_e64 v55, v55, v57, s[42:43]
	v_mul_f32_e32 v56, 0x37800000, v55
	v_cndmask_b32_e32 v55, v55, v56, vcc
	v_cmp_class_f32_e32 vcc, v54, v216
	s_nop 1
	v_cndmask_b32_e32 v54, v55, v54, vcc
	v_div_scale_f32 v55, s[28:29], v54, v54, 1.0
	v_rcp_f32_e32 v56, v55
	v_div_scale_f32 v57, vcc, 1.0, v54, 1.0
	v_fma_f32 v58, -v55, v56, 1.0
	v_fmac_f32_e32 v56, v58, v56
	v_mul_f32_e32 v58, v57, v56
	v_fma_f32 v59, -v55, v58, v57
	v_fmac_f32_e32 v58, v59, v56
	v_fma_f32 v55, -v55, v58, v57
	v_div_fmas_f32 v55, v55, v56, v58
	v_div_fixup_f32 v54, v55, v54, 1.0
	v_pk_fma_f32 v[46:47], v[46:47], v[54:55], v[78:79] op_sel_hi:[1,0,1]
	v_pk_fma_f32 v[44:45], v[44:45], v[54:55], v[76:77] op_sel_hi:[1,0,1]
	v_pk_fma_f32 v[42:43], v[42:43], v[54:55], v[74:75] op_sel_hi:[1,0,1]
	v_pk_fma_f32 v[40:41], v[40:41], v[54:55], v[72:73] op_sel_hi:[1,0,1]
	v_pk_fma_f32 v[34:35], v[34:35], v[54:55], v[66:67] op_sel_hi:[1,0,1]
	v_pk_fma_f32 v[32:33], v[32:33], v[54:55], v[64:65] op_sel_hi:[1,0,1]
	v_pk_fma_f32 v[38:39], v[38:39], v[54:55], v[70:71] op_sel_hi:[1,0,1]
	v_pk_fma_f32 v[36:37], v[36:37], v[54:55], v[68:69] op_sel_hi:[1,0,1]
	v_max_f32_e32 v45, 0, v45
	v_max_f32_e32 v44, 0, v44
	v_max_f32_e32 v47, 0, v47
	v_max_f32_e32 v46, 0, v46
	v_max_f32_e32 v41, 0, v41
	v_max_f32_e32 v40, 0, v40
	v_max_f32_e32 v43, 0, v43
	v_max_f32_e32 v42, 0, v42
	v_max_f32_e32 v33, 0, v33
	v_max_f32_e32 v32, 0, v32
	v_max_f32_e32 v35, 0, v35
	v_max_f32_e32 v34, 0, v34
	v_max_f32_e32 v37, 0, v37
	v_max_f32_e32 v36, 0, v36
	v_max_f32_e32 v39, 0, v39
	v_max_f32_e32 v38, 0, v38
	v_pk_mul_f32 v[46:47], v[46:47], v[46:47]
	v_pk_mul_f32 v[44:45], v[44:45], v[44:45]
	v_pk_mul_f32 v[42:43], v[42:43], v[42:43]
	v_pk_mul_f32 v[40:41], v[40:41], v[40:41]
	v_pk_mul_f32 v[54:55], v[34:35], v[34:35]
	v_pk_mul_f32 v[56:57], v[32:33], v[32:33]
	v_cvt_pk_bf16_f32 v32, v44, v45
	v_cvt_pk_bf16_f32 v33, v46, v47
	v_cvt_pk_bf16_f32 v34, v40, v41
	v_cvt_pk_bf16_f32 v35, v42, v43
	v_pk_mul_f32 v[38:39], v[38:39], v[38:39]
	v_pk_mul_f32 v[36:37], v[36:37], v[36:37]
	global_store_dwordx4 v[50:51], v[32:35], off
	s_nop 1
	v_cvt_pk_bf16_f32 v32, v36, v37
	v_cvt_pk_bf16_f32 v33, v38, v39
	v_cvt_pk_bf16_f32 v34, v56, v57
	v_cvt_pk_bf16_f32 v35, v54, v55
	global_store_dwordx4 v[50:51], v[32:35], off offset:256
	global_load_dwordx4 v[32:35], v[52:53], off
	s_nop 0
	global_load_dwordx4 v[36:39], v[52:53], off offset:16
	s_waitcnt vmcnt(1)
;     __device__ __forceinline__ void operator()(const f32x4 (&acc)[2][2][4][2], const Unit& u, int wr, int wc, int fr, int fq) const {
;     ...
;             for (int m = 0; m < 4; ++m) { const int row = row0 + ai * HALF + m * 16; bf16_t* rowp = base + (size_t)row * ldc + col0;
;                 float inv = 1.f;
;                 if (ss) { const f32x4* sp = (const f32x4*)(ss + (size_t)row * 32 + fq * 8); const f32x4 p0 = sp[0], p1 = sp[1];
;                     float s = ((p0[0] + p0[1]) + (p0[2] + p0[3])) + ((p1[0] + p1[1]) + (p1[2] + p1[3]));
;                     s += __shfl_xor(s, 16); s += __shfl_xor(s, 32); inv = 1.0f / sqrtf(s * (1.f / 2048.f) + 1e-6f); }
;                 f32x4 va[2][2];
; #pragma unroll
;                 for (int bj = 0; bj < 2; ++bj) { f32x4 v0 = acc[ai][bj][m][0], v1 = acc[ai][bj][m][1];
;                     if (ss) { v0 = v0 * inv + swv[bj][0]; v1 = v1 * inv + swv[bj][1]; }
;                     if (ACT == 2) { v0 = __builtin_elementwise_max(v0, (f32x4){0.f, 0.f, 0.f, 0.f}); v1 = __builtin_elementwise_max(v1, (f32x4){0.f, 0.f, 0.f, 0.f}); v0 = v0 * v0; v1 = v1 * v1; }
;                     v0 = v0 * sc; v1 = v1 * sc;
;                     if (do_nrm) { float s2 = ((v0[0] * v0[0] + v0[1] * v0[1]) + (v0[2] * v0[2] + v0[3] * v0[3])) + ((v1[0] * v1[0] + v1[1] * v1[1]) + (v1[2] * v1[2] + v1[3] * v1[3]));
;                         s2 += __shfl_xor(s2, 16); s2 += __shfl_xor(s2, 32);
;                         if (fq == 0) nrm[((size_t)(((u.pn >> 3) * 4 + (row >> 12)) * 16 + (u.pn & 7) * 2 + bj) * 4096 + (row & 4095)) * 4 + wc] = s2; }
;                     va[bj][0] = v0; va[bj][1] = v1; }
;                 if (cu_out != nullptr && u.pn >= cu_from) {
;                     const f32x4 p0 = va[0][0] * va[1][0], p1 = va[0][1] * va[1][1];
;                     u32x4 w; w.x = cvt_pk_bf16(p0[0], p0[1]); w.y = cvt_pk_bf16(p0[2], p0[3]); w.z = cvt_pk_bf16(p1[0], p1[1]); w.w = cvt_pk_bf16(p1[2], p1[3]);
;                     *(u32x4*)(cu_out + (size_t)row * ldc + (u.pn - cu_from) * HALF + wc * 32 + 8 * fq) = w;
;                 } else {
; #pragma unroll
;                     for (int bj = 0; bj < 2; ++bj) { const f32x4 v0 = va[bj][0], v1 = va[bj][1];
;                         u32x4 w; w.x = cvt_pk_bf16(v0[0], v0[1]); w.y = cvt_pk_bf16(v0[2], v0[3]); w.z = cvt_pk_bf16(v1[0], v1[1]); w.w = cvt_pk_bf16(v1[2], v1[3]);
	v_mov_b32_e32 v40, v32
	s_waitcnt vmcnt(0)
	v_mov_b32_e32 v41, v36
	v_mov_b32_e32 v36, v33
	v_mov_b32_e32 v32, v34
	v_mov_b32_e32 v33, v38
	v_mov_b32_e32 v38, v35
	v_pk_add_f32 v[34:35], v[40:41], v[36:37]
	v_pk_add_f32 v[32:33], v[32:33], v[38:39]
	s_nop 0
	v_pk_add_f32 v[32:33], v[34:35], v[32:33]
	s_nop 0
	v_add_f32_e32 v32, v32, v33
	ds_bpermute_b32 v33, v167, v32
	s_waitcnt lgkmcnt(0)
	v_add_f32_e32 v34, v32, v33
	ds_bpermute_b32 v35, v168, v34
	v_add_u32_e32 v32, 0xb0, v158
	v_ashrrev_i32_e32 v33, 31, v32
	v_lshlrev_b64 v[36:37], 7, v[32:33]
	v_lshl_add_u64 v[36:37], v[150:151], 0, v[36:37]
	s_waitcnt lgkmcnt(0)
	v_add_f32_e32 v34, v34, v35
	v_fmamk_f32 v34, v34, 0x3a000000, v215
	v_mul_f32_e32 v35, 0x4f800000, v34
	v_cmp_gt_f32_e32 vcc, s5, v34
	s_nop 1
	v_cndmask_b32_e32 v38, v34, v35, vcc
	v_sqrt_f32_e32 v39, v38
	v_lshlrev_b64 v[34:35], 14, v[48:49]
	v_lshl_add_u64 v[34:35], v[156:157], 0, v[34:35]
	v_add_u32_e32 v40, -1, v39
	v_add_u32_e32 v41, 1, v39
	v_fma_f32 v42, -v40, v39, v38
	v_fma_f32 v43, -v41, v39, v38
	v_cmp_ge_f32_e64 s[42:43], 0, v42
	s_nop 1
	v_cndmask_b32_e64 v39, v39, v40, s[42:43]
	v_cmp_lt_f32_e64 s[42:43], 0, v43
	s_nop 1
	v_cndmask_b32_e64 v39, v39, v41, s[42:43]
	v_mul_f32_e32 v40, 0x37800000, v39
	v_cndmask_b32_e32 v39, v39, v40, vcc
	v_cmp_class_f32_e32 vcc, v38, v216
	s_nop 1
	v_cndmask_b32_e32 v38, v39, v38, vcc
	v_div_scale_f32 v39, s[28:29], v38, v38, 1.0
	v_rcp_f32_e32 v40, v39
	v_div_scale_f32 v41, vcc, 1.0, v38, 1.0
	v_fma_f32 v42, -v39, v40, 1.0
	v_fmac_f32_e32 v40, v42, v40
	v_mul_f32_e32 v42, v41, v40
	v_fma_f32 v43, -v39, v42, v41
	v_fmac_f32_e32 v42, v43, v40
	v_fma_f32 v39, -v39, v42, v41
	v_div_fmas_f32 v39, v39, v40, v42
	v_div_fixup_f32 v38, v39, v38, 1.0
	v_pk_fma_f32 v[30:31], v[30:31], v[38:39], v[78:79] op_sel_hi:[1,0,1]
	v_pk_fma_f32 v[28:29], v[28:29], v[38:39], v[76:77] op_sel_hi:[1,0,1]
	v_pk_fma_f32 v[26:27], v[26:27], v[38:39], v[74:75] op_sel_hi:[1,0,1]
	v_pk_fma_f32 v[24:25], v[24:25], v[38:39], v[72:73] op_sel_hi:[1,0,1]
	v_pk_fma_f32 v[18:19], v[18:19], v[38:39], v[66:67] op_sel_hi:[1,0,1]
	v_pk_fma_f32 v[16:17], v[16:17], v[38:39], v[64:65] op_sel_hi:[1,0,1]
	v_pk_fma_f32 v[22:23], v[22:23], v[38:39], v[70:71] op_sel_hi:[1,0,1]
	v_pk_fma_f32 v[20:21], v[20:21], v[38:39], v[68:69] op_sel_hi:[1,0,1]
	v_max_f32_e32 v29, 0, v29
	v_max_f32_e32 v28, 0, v28
	v_max_f32_e32 v31, 0, v31
	v_max_f32_e32 v30, 0, v30
	v_max_f32_e32 v25, 0, v25
	v_max_f32_e32 v24, 0, v24
	v_max_f32_e32 v27, 0, v27
	v_max_f32_e32 v26, 0, v26
	v_max_f32_e32 v17, 0, v17
	v_max_f32_e32 v16, 0, v16
	v_max_f32_e32 v19, 0, v19
	v_max_f32_e32 v18, 0, v18
	v_max_f32_e32 v21, 0, v21
	v_max_f32_e32 v20, 0, v20
	v_max_f32_e32 v23, 0, v23
	v_max_f32_e32 v22, 0, v22
	v_pk_mul_f32 v[30:31], v[30:31], v[30:31]
	v_pk_mul_f32 v[28:29], v[28:29], v[28:29]
	v_pk_mul_f32 v[26:27], v[26:27], v[26:27]
	v_pk_mul_f32 v[24:25], v[24:25], v[24:25]
	v_pk_mul_f32 v[38:39], v[18:19], v[18:19]
	v_pk_mul_f32 v[40:41], v[16:17], v[16:17]
	v_cvt_pk_bf16_f32 v16, v28, v29
	v_cvt_pk_bf16_f32 v17, v30, v31
	v_cvt_pk_bf16_f32 v18, v24, v25
	v_cvt_pk_bf16_f32 v19, v26, v27
	v_pk_mul_f32 v[22:23], v[22:23], v[22:23]
	v_pk_mul_f32 v[20:21], v[20:21], v[20:21]
	global_store_dwordx4 v[34:35], v[16:19], off
	s_nop 1
	v_cvt_pk_bf16_f32 v16, v20, v21
	v_cvt_pk_bf16_f32 v17, v22, v23
	v_cvt_pk_bf16_f32 v18, v40, v41
	v_cvt_pk_bf16_f32 v19, v38, v39
	global_store_dwordx4 v[34:35], v[16:19], off offset:256
	global_load_dwordx4 v[16:19], v[36:37], off
	s_nop 0
	global_load_dwordx4 v[20:23], v[36:37], off offset:16
	s_waitcnt vmcnt(1)
	v_mov_b32_e32 v24, v16
	s_waitcnt vmcnt(0)
	v_mov_b32_e32 v25, v20
	v_mov_b32_e32 v20, v17
	v_mov_b32_e32 v16, v18
	v_mov_b32_e32 v17, v22
	v_mov_b32_e32 v22, v19
	v_pk_add_f32 v[18:19], v[24:25], v[20:21]
	v_pk_add_f32 v[16:17], v[16:17], v[22:23]
	s_nop 0
	v_pk_add_f32 v[16:17], v[18:19], v[16:17]
	s_nop 0
	v_add_f32_e32 v16, v16, v17
	ds_bpermute_b32 v17, v167, v16
	s_waitcnt lgkmcnt(0)
	v_add_f32_e32 v16, v16, v17
	ds_bpermute_b32 v17, v168, v16
	s_waitcnt lgkmcnt(0)
	v_add_f32_e32 v16, v16, v17
	v_fmamk_f32 v16, v16, 0x3a000000, v215
	v_mul_f32_e32 v17, 0x4f800000, v16
	v_cmp_gt_f32_e32 vcc, s5, v16
	s_nop 1
	v_cndmask_b32_e32 v18, v16, v17, vcc
	v_sqrt_f32_e32 v19, v18
	v_lshlrev_b64 v[16:17], 14, v[32:33]
	v_lshl_add_u64 v[16:17], v[156:157], 0, v[16:17]
	v_add_u32_e32 v20, -1, v19
	v_add_u32_e32 v21, 1, v19
	v_fma_f32 v22, -v20, v19, v18
	v_fma_f32 v23, -v21, v19, v18
	v_cmp_ge_f32_e64 s[42:43], 0, v22
	s_nop 1
	v_cndmask_b32_e64 v19, v19, v20, s[42:43]
	v_cmp_lt_f32_e64 s[42:43], 0, v23
	s_nop 1
	v_cndmask_b32_e64 v19, v19, v21, s[42:43]
	v_mul_f32_e32 v20, 0x37800000, v19
	v_cndmask_b32_e32 v19, v19, v20, vcc
	v_cmp_class_f32_e32 vcc, v18, v216
	s_nop 1
	v_cndmask_b32_e32 v18, v19, v18, vcc
	v_div_scale_f32 v19, s[28:29], v18, v18, 1.0
	v_rcp_f32_e32 v20, v19
	v_div_scale_f32 v21, vcc, 1.0, v18, 1.0
	v_fma_f32 v22, -v19, v20, 1.0
	v_fmac_f32_e32 v20, v22, v20
	v_mul_f32_e32 v22, v21, v20
	v_fma_f32 v23, -v19, v22, v21
	v_fmac_f32_e32 v22, v23, v20
	v_fma_f32 v19, -v19, v22, v21
	v_div_fmas_f32 v19, v19, v20, v22
	v_div_fixup_f32 v18, v19, v18, 1.0
	v_pk_fma_f32 v[14:15], v[14:15], v[18:19], v[78:79] op_sel_hi:[1,0,1]
	v_pk_fma_f32 v[12:13], v[12:13], v[18:19], v[76:77] op_sel_hi:[1,0,1]
	v_pk_fma_f32 v[10:11], v[10:11], v[18:19], v[74:75] op_sel_hi:[1,0,1]
	v_pk_fma_f32 v[8:9], v[8:9], v[18:19], v[72:73] op_sel_hi:[1,0,1]
	v_pk_fma_f32 v[2:3], v[2:3], v[18:19], v[66:67] op_sel_hi:[1,0,1]
	v_pk_fma_f32 v[0:1], v[0:1], v[18:19], v[64:65] op_sel_hi:[1,0,1]
	v_pk_fma_f32 v[6:7], v[6:7], v[18:19], v[70:71] op_sel_hi:[1,0,1]
	v_pk_fma_f32 v[4:5], v[4:5], v[18:19], v[68:69] op_sel_hi:[1,0,1]
	v_max_f32_e32 v13, 0, v13
	v_max_f32_e32 v12, 0, v12
	v_max_f32_e32 v15, 0, v15
	v_max_f32_e32 v14, 0, v14
	v_max_f32_e32 v9, 0, v9
	v_max_f32_e32 v8, 0, v8
	v_max_f32_e32 v11, 0, v11
	v_max_f32_e32 v10, 0, v10
	v_max_f32_e32 v1, 0, v1
	v_max_f32_e32 v0, 0, v0
	v_max_f32_e32 v3, 0, v3
	v_max_f32_e32 v2, 0, v2
	s_andn2_b64 vcc, exec, s[40:41]
	v_max_f32_e32 v5, 0, v5
	v_max_f32_e32 v4, 0, v4
	v_max_f32_e32 v7, 0, v7
	v_max_f32_e32 v6, 0, v6
	v_pk_mul_f32 v[14:15], v[14:15], v[14:15]
	v_pk_mul_f32 v[12:13], v[12:13], v[12:13]
	v_pk_mul_f32 v[10:11], v[10:11], v[10:11]
	v_pk_mul_f32 v[8:9], v[8:9], v[8:9]
	v_pk_mul_f32 v[18:19], v[2:3], v[2:3]
	v_pk_mul_f32 v[20:21], v[0:1], v[0:1]
	v_cvt_pk_bf16_f32 v0, v12, v13
	v_cvt_pk_bf16_f32 v1, v14, v15
	v_cvt_pk_bf16_f32 v2, v8, v9
	v_cvt_pk_bf16_f32 v3, v10, v11
	s_mov_b64 s[40:41], -1
	v_pk_mul_f32 v[6:7], v[6:7], v[6:7]
	v_pk_mul_f32 v[4:5], v[4:5], v[4:5]
	global_store_dwordx4 v[16:17], v[0:3], off
	s_nop 1
	v_cvt_pk_bf16_f32 v0, v4, v5
	v_cvt_pk_bf16_f32 v1, v6, v7
	v_cvt_pk_bf16_f32 v2, v20, v21
	v_cvt_pk_bf16_f32 v3, v18, v19
	global_store_dwordx4 v[16:17], v[0:3], off offset:256
	s_cbranch_vccnz .LBB0_47
; #define PG8_BAR __builtin_amdgcn_s_barrier()
; template <class Epi, class Sched, bool ALIGN_EPI = false, bool SP2 = false>
; __device__ __forceinline__ void gemm_phase(PG8_LAS unsigned char* lds, const Gemm g, const Sched& S, const Epi& E) {
;     ...
;         if (!has_next) break;
; #pragma unroll
;         for (int a = 0; a < 2; ++a)
; #pragma unroll
;             for (int b = 0; b < 2; ++b)
; #pragma unroll
;                 for (int m = 0; m < 4; ++m)
; #pragma unroll
;                     for (int n = 0; n < 2; ++n) acc[a][b][m][n] = (f32x4){0.f, 0.f, 0.f, 0.f};
;         cur = nxt; cA = nA; cB = nB; ++ui;
;         if constexpr (ALIGN_EPI) { if (wr == 1) PG8_BAR; }
	s_andn2_b64 vcc, exec, s[14:15]
	s_cbranch_vccnz .LBB0_46
	s_barrier
	s_branch .LBB0_46
	s_nop 0
	s_nop 0
	s_nop 0
	s_nop 0
	s_nop 0
	s_nop 0
	s_nop 0
	s_nop 0
	s_nop 0
	s_nop 0
	s_nop 0
	s_nop 0
	s_nop 0
	s_nop 0

; #define LAS __attribute__((address_space(3)))
; __global__ void __launch_bounds__(NTHREADS, 2) fwd_mega(Args a) {
;     extern __shared__ __attribute__((aligned(16))) unsigned char lds[];
;     LAS unsigned char* L = (LAS unsigned char*)lds;
;     const int G = gridDim.x, ngw = G * NWAVES;
;     const kargp_t kp = (kargp_t)__builtin_amdgcn_kernarg_segment_ptr();
	.amdhsa_kernel _Z8fwd_mega4Args
		.amdhsa_group_segment_fixed_size 0
		.amdhsa_private_segment_fixed_size 0
		.amdhsa_kernarg_size 400
		.amdhsa_user_sgpr_count 2
		.amdhsa_user_sgpr_dispatch_ptr 0
		.amdhsa_user_sgpr_queue_ptr 0
		.amdhsa_user_sgpr_kernarg_segment_ptr 1
		.amdhsa_user_sgpr_dispatch_id 0
		.amdhsa_user_sgpr_kernarg_preload_length 0
		.amdhsa_user_sgpr_kernarg_preload_offset 0
		.amdhsa_user_sgpr_private_segment_size 0
		.amdhsa_uses_dynamic_stack 0
		.amdhsa_enable_private_segment 0
		.amdhsa_system_sgpr_workgroup_id_x 1
		.amdhsa_system_sgpr_workgroup_id_y 0
		.amdhsa_system_sgpr_workgroup_id_z 0
		.amdhsa_system_sgpr_workgroup_info 0
		.amdhsa_system_vgpr_workitem_id 2
		.amdhsa_next_free_vgpr 256
		.amdhsa_next_free_sgpr 102
		.amdhsa_accum_offset 256
		.amdhsa_reserve_vcc 1
		.amdhsa_float_round_mode_32 0
		.amdhsa_float_round_mode_16_64 0
		.amdhsa_float_denorm_mode_32 3
		.amdhsa_float_denorm_mode_16_64 3
		.amdhsa_dx10_clamp 1
		.amdhsa_ieee_mode 1
		.amdhsa_fp16_overflow 0
		.amdhsa_tg_split 0
		.amdhsa_exception_fp_ieee_invalid_op 0
		.amdhsa_exception_fp_denorm_src 0
		.amdhsa_exception_fp_ieee_div_zero 0
		.amdhsa_exception_fp_ieee_overflow 0
		.amdhsa_exception_fp_ieee_underflow 0
		.amdhsa_exception_fp_ieee_inexact 0
		.amdhsa_exception_int_div_zero 0
	.end_amdhsa_kernel

; __global__ void __launch_bounds__(NTHREADS, 2) fwd_mega(Args a) {
amdhsa.kernels:
  - .agpr_count:     0
    .args:
      - .offset:         0
        .size:           144
        .value_kind:     by_value
      - .offset:         144
        .size:           4
        .value_kind:     hidden_block_count_x
      - .offset:         148
        .size:           4
        .value_kind:     hidden_block_count_y
      - .offset:         152
        .size:           4
        .value_kind:     hidden_block_count_z
      - .offset:         156
        .size:           2
        .value_kind:     hidden_group_size_x
      - .offset:         158
        .size:           2
        .value_kind:     hidden_group_size_y
      - .offset:         160
        .size:           2
        .value_kind:     hidden_group_size_z
      - .offset:         162
        .size:           2
        .value_kind:     hidden_remainder_x
      - .offset:         164
        .size:           2
        .value_kind:     hidden_remainder_y
      - .offset:         166
        .size:           2
        .value_kind:     hidden_remainder_z
      - .offset:         184
        .size:           8
        .value_kind:     hidden_global_offset_x
      - .offset:         192
        .size:           8
        .value_kind:     hidden_global_offset_y
      - .offset:         200
        .size:           8
        .value_kind:     hidden_global_offset_z
      - .offset:         208
        .size:           2
        .value_kind:     hidden_grid_dims
      - .offset:         232
        .size:           8
        .value_kind:     hidden_multigrid_sync_arg
      - .offset:         264
        .size:           4
        .value_kind:     hidden_dynamic_lds_size
    .group_segment_fixed_size: 0
    .kernarg_segment_align: 8
    .kernarg_segment_size: 400
    .language:       OpenCL C
    .language_version:
      - 2
      - 0
    .max_flat_workgroup_size: 512
    .name:           _Z8fwd_mega4Args
    .private_segment_fixed_size: 0
    .sgpr_count:     108
    .sgpr_spill_count: 162
    .symbol:         _Z8fwd_mega4Args.kd
    .uniform_work_group_size: 1
    .uses_dynamic_stack: false
    .vgpr_count:     256
    .vgpr_spill_count: 0
    .wavefront_size: 64
